# u-pass gather addresses via ds_bpermute (8 instrs per load pair down to 3), stacked on peer_v rewrite and odd-A stagger
# speedup vs baseline: 1.0022x; 1.0022x over previous
; __device__ __forceinline__ int otid() { int t = threadIdx.x; asm volatile("" : "+v"(t)); return t; }
; __device__ void peer_u(const P& p, int layer, int tok, char* smem, const int (&eidx)[2], const float (&gate)[2],
;                        const u32x4 (&scnext)[4], const bool has_next, int (&eidx_n)[2], float (&gate_n)[2]) {
;     ...
;   const int tid_ = otid(); const int lane = tid_ & 63, li = lane & 15, rw = lane >> 4;
;   const unsigned char* xn8 = (const unsigned char*)(ws + OFF_AO) + (32ull << 20) + (size_t)tok * 1024;
;   i32x8 tq[8];
; #pragma unroll
;   for (int s8 = 0; s8 < 8; ++s8) {
;     const u32x4 lo = *(const u32x4*)(xn8 + s8 * 128 + rw * 16);
;     const u32x4 hi = *(const u32x4*)(xn8 + s8 * 128 + 64 + rw * 16);
;     tq[s8] = (i32x8){(int)lo.x, (int)lo.y, (int)lo.z, (int)lo.w, (int)hi.x, (int)hi.y, (int)hi.z, (int)hi.w};
;   }
;   const unsigned char* U4 = (const unsigned char*)(ws + OFF_U) + (size_t)layer * 16384 * 512;
;   const unsigned char* V4 = (const unsigned char*)(ws + OFF_U) + (size_t)(4 + layer) * 16384 * 512;
;   const float* SU = (const float*)(ws + OFF_V) + (size_t)layer * 16384;
;   const float* SV = (const float*)(ws + OFF_V) + (size_t)(4 + layer) * 16384;
;   char* lw = smem + (tid_ >> 6) * 8704;
;   float wreg[2];
; #pragma unroll
;   for (int h2 = 0; h2 < 2; ++h2) {
;     const float su = SU[eidx[h2]], sv = SV[eidx[h2]];
;     float hreg = 0.f;
;     for (int b2 = 0; b2 < 2; ++b2) {
;       u32x4 uu[16];
;       const int lh = lane >> 5, l5 = lane & 31;
; #pragma unroll
;       for (int q = 0; q < 16; ++q) {
;         const int e0 = __builtin_amdgcn_readlane(eidx[h2], b2 * 32 + 2 * q);
;         const int e1 = __builtin_amdgcn_readlane(eidx[h2], b2 * 32 + 2 * q + 1);
;         const int e = lh ? e1 : e0;
;         uu[q] = ((const u32x4*)(U4 + (size_t)e * 512))[l5];
.LBB0_1001:
	v_lshrrev_b32_e32 v221, 5, v243
	v_lshlrev_b32_e32 v221, 2, v221
	v_mov_b32_e32 v223, 0
	v_mov_b32_e32 v225, 0
	v_mov_b32_e32 v227, 0
	v_mov_b32_e32 v229, 0
	v_mov_b32_e32 v231, 0
	v_mov_b32_e32 v233, 0
	v_mov_b32_e32 v235, 0
	v_mov_b32_e32 v237, 0
	v_readlane_b32 s0, v255, 46
	v_readlane_b32 s1, v255, 47
	s_andn2_b64 vcc, exec, s[0:1]
	s_nop 0
	v_cndmask_b32_e64 v0, 0, 1, s[0:1]
	v_cmp_ne_u32_e64 s[6:7], 1, v0
	s_cbranch_vccnz .LBB0_1045
	v_lshlrev_b32_e32 v0, 4, v25
	v_writelane_b32 v255, s6, 62
	v_and_b32_e32 v0, 0xf0, v0
	v_lshl_add_u64 v[20:21], s[42:43], 0, v[0:1]
	v_writelane_b32 v255, s7, 63
	v_lshlrev_b32_e32 v0, 5, v24
	v_readlane_b32 s0, v255, 60
	v_and_b32_e32 v0, 0x600, v0
	v_readlane_b32 s1, v255, 61
	v_lshl_add_u64 v[150:151], v[20:21], 0, v[0:1]
	v_mov_b32_e32 v0, v1
	s_mov_b32 s65, s86
	s_mov_b32 s79, s77
	s_lshl_b64 s[48:49], s[54:55], 23
	s_lshl_b64 s[56:57], s[54:55], 16
	s_lshl_b32 s66, s0, 16
	v_mov_b32_e32 v156, v1
	v_mov_b32_e32 v157, v1
	v_readlane_b32 s0, v255, 53
	v_mov_b64_e32 v[158:159], v[0:1]
	v_readlane_b32 s1, v255, 54

; __device__ __forceinline__ void peer_topk(const u32x4 (&scv)[4], const int lane, int (&eidx)[2], float (&gate)[2]) {
;     ...
;     for (int rd = 0; rd < 16; ++rd) {
;       const unsigned wk = rowmax_u(k[0]);
;       if (li == rd) keep = wk;
;       const bool win = (k[0] == wk);
;       k[0] = win ? k[1] : k[0]; k[1] = win ? k[2] : k[1]; k[2] = win ? k[3] : k[2]; k[3] = win ? k[4] : k[3];
;       k[4] = win ? k[5] : k[4]; k[5] = win ? k[6] : k[5]; k[6] = win ? k[7] : k[6]; k[7] = win ? 0u : k[7];
;     }
; __device__ void peer_u(const P& p, int layer, int tok, char* smem, const int (&eidx)[2], const float (&gate)[2],
;                        const u32x4 (&scnext)[4], const bool has_next, int (&eidx_n)[2], float (&gate_n)[2]) {
;     ...
;     for (int b2 = 0; b2 < 2; ++b2) {
;       u32x4 uu[16];
;       const int lh = lane >> 5, l5 = lane & 31;
; #pragma unroll
;       for (int q = 0; q < 16; ++q) {
;         const int e0 = __builtin_amdgcn_readlane(eidx[h2], b2 * 32 + 2 * q);
;         const int e1 = __builtin_amdgcn_readlane(eidx[h2], b2 * 32 + 2 * q + 1);
;         const int e = lh ? e1 : e0;
;         uu[q] = ((const u32x4*)(U4 + (size_t)e * 512))[l5];
;       }
;       if (h2 == 0 && b2 == 0 && has_next) peer_topk(scnext, lane, eidx_n, gate_n);
.LBB0_1006:
	s_lshl_b32 s0, s7, 5
	v_mov_b32_e32 v252, s0
	v_lshl_add_u32 v252, v252, 2, v221
	v_lshlrev_b32_e32 v253, 9, v2
	v_add_u32_e32 v222, 0, v252
	ds_bpermute_b32 v222, v222, v253
	v_add_u32_e32 v224, 8, v252
	ds_bpermute_b32 v224, v224, v253
	v_add_u32_e32 v226, 16, v252
	ds_bpermute_b32 v226, v226, v253
	v_add_u32_e32 v228, 24, v252
	ds_bpermute_b32 v228, v228, v253
	v_add_u32_e32 v230, 32, v252
	ds_bpermute_b32 v230, v230, v253
	v_add_u32_e32 v232, 40, v252
	ds_bpermute_b32 v232, v232, v253
	v_add_u32_e32 v234, 48, v252
	ds_bpermute_b32 v234, v234, v253
	v_add_u32_e32 v236, 56, v252
	ds_bpermute_b32 v236, v236, v253
	s_nop 0
	s_waitcnt lgkmcnt(0)
	v_lshl_add_u64 v[84:85], v[222:223], 0, v[154:155]
	v_lshl_add_u64 v[88:89], v[224:225], 0, v[154:155]
	v_lshl_add_u64 v[92:93], v[226:227], 0, v[154:155]
	global_load_dwordx4 v[84:87], v[84:85], off
	s_nop 0
	global_load_dwordx4 v[88:91], v[88:89], off
	v_lshl_add_u64 v[94:95], v[228:229], 0, v[154:155]
	global_load_dwordx4 v[100:103], v[92:93], off
	global_load_dwordx4 v[104:107], v[94:95], off
	v_lshl_add_u64 v[92:93], v[230:231], 0, v[154:155]
	v_lshl_add_u64 v[94:95], v[232:233], 0, v[154:155]
	global_load_dwordx4 v[116:119], v[92:93], off
	global_load_dwordx4 v[120:123], v[94:95], off
	v_lshl_add_u64 v[92:93], v[234:235], 0, v[154:155]
	v_lshl_add_u64 v[94:95], v[236:237], 0, v[154:155]
	v_lshlrev_b32_e32 v253, 9, v2
	v_add_u32_e32 v222, 64, v252
	ds_bpermute_b32 v222, v222, v253
	v_add_u32_e32 v224, 72, v252
	ds_bpermute_b32 v224, v224, v253
	v_add_u32_e32 v226, 80, v252
	ds_bpermute_b32 v226, v226, v253
	v_add_u32_e32 v228, 88, v252
	ds_bpermute_b32 v228, v228, v253
	v_add_u32_e32 v230, 96, v252
	ds_bpermute_b32 v230, v230, v253
	v_add_u32_e32 v232, 104, v252
	ds_bpermute_b32 v232, v232, v253
	v_add_u32_e32 v234, 112, v252
	ds_bpermute_b32 v234, v234, v253
	v_add_u32_e32 v236, 120, v252
	ds_bpermute_b32 v236, v236, v253
	global_load_dwordx4 v[132:135], v[92:93], off
	global_load_dwordx4 v[136:139], v[94:95], off
	s_nop 0
	s_waitcnt lgkmcnt(0)
	v_lshl_add_u64 v[92:93], v[222:223], 0, v[154:155]
	v_lshl_add_u64 v[96:97], v[224:225], 0, v[154:155]
	v_lshl_add_u64 v[108:109], v[226:227], 0, v[154:155]
	v_lshl_add_u64 v[112:113], v[228:229], 0, v[154:155]
	v_lshl_add_u64 v[124:125], v[230:231], 0, v[154:155]
	v_lshl_add_u64 v[128:129], v[232:233], 0, v[154:155]
	v_lshl_add_u64 v[140:141], v[234:235], 0, v[154:155]
	v_lshl_add_u64 v[144:145], v[236:237], 0, v[154:155]
	global_load_dwordx4 v[92:95], v[92:93], off
	s_nop 0
	global_load_dwordx4 v[96:99], v[96:97], off
	s_nop 0
	global_load_dwordx4 v[108:111], v[108:109], off
	s_nop 0
	global_load_dwordx4 v[112:115], v[112:113], off
	s_nop 0
	global_load_dwordx4 v[124:127], v[124:125], off
	s_nop 0
	global_load_dwordx4 v[128:131], v[128:129], off
	s_nop 0
	global_load_dwordx4 v[140:143], v[140:141], off
	s_nop 0
	global_load_dwordx4 v[144:147], v[144:145], off
	s_and_b64 s[0:1], s[54:55], s[62:63]
	s_andn2_b64 vcc, exec, s[0:1]
	s_cbranch_vccnz .LBB0_1008
	v_max_u32_dpp v156, v173, v173 row_ror:1 row_mask:0xf bank_mask:0xf bound_ctrl:1
	s_nop 1
	v_max_u32_dpp v156, v156, v156 row_ror:2 row_mask:0xf bank_mask:0xf bound_ctrl:1
	s_nop 1
	v_max_u32_dpp v156, v156, v156 row_ror:4 row_mask:0xf bank_mask:0xf bound_ctrl:1
	s_nop 1
	v_max_u32_dpp v156, v156, v156 row_ror:8 row_mask:0xf bank_mask:0xf bound_ctrl:1
	v_cmp_eq_u32_e32 vcc, v173, v156
	v_cndmask_b32_e64 v157, 0, v156, s[12:13]
	s_nop 0
	v_cndmask_b32_e32 v156, v173, v175, vcc
	v_cndmask_b32_e32 v158, v175, v176, vcc
	v_cndmask_b32_e32 v159, v176, v177, vcc
	v_max_u32_dpp v215, v156, v156 row_ror:1 row_mask:0xf bank_mask:0xf bound_ctrl:1
	v_cndmask_b32_e32 v160, v177, v178, vcc
	v_cndmask_b32_e32 v161, v178, v179, vcc
	v_max_u32_dpp v215, v215, v215 row_ror:2 row_mask:0xf bank_mask:0xf bound_ctrl:1
	v_cndmask_b32_e32 v206, v179, v180, vcc
	v_cndmask_b32_e32 v207, v180, v174, vcc
	v_max_u32_dpp v215, v215, v215 row_ror:4 row_mask:0xf bank_mask:0xf bound_ctrl:1
	v_cndmask_b32_e64 v213, v174, 0, vcc
	s_nop 0
	v_max_u32_dpp v215, v215, v215 row_ror:8 row_mask:0xf bank_mask:0xf bound_ctrl:1
	v_cmp_eq_u32_e32 vcc, v156, v215
	v_cndmask_b32_e64 v157, v157, v215, s[14:15]
	s_nop 0
	v_cndmask_b32_e32 v156, v156, v158, vcc
	v_cndmask_b32_e32 v158, v158, v159, vcc
	v_cndmask_b32_e32 v159, v159, v160, vcc
	v_max_u32_dpp v215, v156, v156 row_ror:1 row_mask:0xf bank_mask:0xf bound_ctrl:1
	v_cndmask_b32_e32 v160, v160, v161, vcc
	v_cndmask_b32_e32 v161, v161, v206, vcc
	v_max_u32_dpp v215, v215, v215 row_ror:2 row_mask:0xf bank_mask:0xf bound_ctrl:1
	v_cndmask_b32_e32 v206, v206, v207, vcc
	v_cndmask_b32_e32 v207, v207, v213, vcc
	v_max_u32_dpp v215, v215, v215 row_ror:4 row_mask:0xf bank_mask:0xf bound_ctrl:1
	v_cndmask_b32_e64 v213, v213, 0, vcc
	s_nop 0
	v_max_u32_dpp v215, v215, v215 row_ror:8 row_mask:0xf bank_mask:0xf bound_ctrl:1
	v_cmp_eq_u32_e32 vcc, v156, v215
	v_cndmask_b32_e64 v157, v157, v215, s[16:17]
	s_nop 0
	v_cndmask_b32_e32 v156, v156, v158, vcc
	v_cndmask_b32_e32 v158, v158, v159, vcc
	v_cndmask_b32_e32 v159, v159, v160, vcc
	v_max_u32_dpp v215, v156, v156 row_ror:1 row_mask:0xf bank_mask:0xf bound_ctrl:1
	v_cndmask_b32_e32 v160, v160, v161, vcc
	v_cndmask_b32_e32 v161, v161, v206, vcc
	v_max_u32_dpp v215, v215, v215 row_ror:2 row_mask:0xf bank_mask:0xf bound_ctrl:1
	v_cndmask_b32_e32 v206, v206, v207, vcc
	v_cndmask_b32_e32 v207, v207, v213, vcc
	v_max_u32_dpp v215, v215, v215 row_ror:4 row_mask:0xf bank_mask:0xf bound_ctrl:1
	v_cndmask_b32_e64 v213, v213, 0, vcc
	s_nop 0
	v_max_u32_dpp v215, v215, v215 row_ror:8 row_mask:0xf bank_mask:0xf bound_ctrl:1
	v_cmp_eq_u32_e32 vcc, v156, v215
; __device__ __forceinline__ void peer_topk(const u32x4 (&scv)[4], const int lane, int (&eidx)[2], float (&gate)[2]) {
;     ...
;     for (int rd = 0; rd < 16; ++rd) {
;       const unsigned wk = rowmax_u(k[0]);
;       if (li == rd) keep = wk;
;       const bool win = (k[0] == wk);
;       k[0] = win ? k[1] : k[0]; k[1] = win ? k[2] : k[1]; k[2] = win ? k[3] : k[2]; k[3] = win ? k[4] : k[3];
;       k[4] = win ? k[5] : k[4]; k[5] = win ? k[6] : k[5]; k[6] = win ? k[7] : k[6]; k[7] = win ? 0u : k[7];
;     }
;     res[pp] = keep;
	v_cndmask_b32_e64 v157, v157, v215, s[18:19]
	s_nop 0
	v_cndmask_b32_e32 v156, v156, v158, vcc
	v_cndmask_b32_e32 v158, v158, v159, vcc
	v_cndmask_b32_e32 v159, v159, v160, vcc
	v_max_u32_dpp v215, v156, v156 row_ror:1 row_mask:0xf bank_mask:0xf bound_ctrl:1
	v_cndmask_b32_e32 v160, v160, v161, vcc
	v_cndmask_b32_e32 v161, v161, v206, vcc
	v_max_u32_dpp v215, v215, v215 row_ror:2 row_mask:0xf bank_mask:0xf bound_ctrl:1
	v_cndmask_b32_e32 v206, v206, v207, vcc
	v_cndmask_b32_e32 v207, v207, v213, vcc
	v_max_u32_dpp v215, v215, v215 row_ror:4 row_mask:0xf bank_mask:0xf bound_ctrl:1
	v_cndmask_b32_e64 v213, v213, 0, vcc
	s_nop 0
	v_max_u32_dpp v215, v215, v215 row_ror:8 row_mask:0xf bank_mask:0xf bound_ctrl:1
	v_cmp_eq_u32_e32 vcc, v156, v215
	v_cndmask_b32_e64 v157, v157, v215, s[20:21]
	s_nop 0
	v_cndmask_b32_e32 v156, v156, v158, vcc
	v_cndmask_b32_e32 v158, v158, v159, vcc
	v_cndmask_b32_e32 v159, v159, v160, vcc
	v_max_u32_dpp v215, v156, v156 row_ror:1 row_mask:0xf bank_mask:0xf bound_ctrl:1
	v_cndmask_b32_e32 v160, v160, v161, vcc
	v_cndmask_b32_e32 v161, v161, v206, vcc
	v_max_u32_dpp v215, v215, v215 row_ror:2 row_mask:0xf bank_mask:0xf bound_ctrl:1
	v_cndmask_b32_e32 v206, v206, v207, vcc
	v_cndmask_b32_e32 v207, v207, v213, vcc
	v_max_u32_dpp v215, v215, v215 row_ror:4 row_mask:0xf bank_mask:0xf bound_ctrl:1
	v_cndmask_b32_e64 v213, v213, 0, vcc
	s_nop 0
	v_max_u32_dpp v215, v215, v215 row_ror:8 row_mask:0xf bank_mask:0xf bound_ctrl:1
	v_cmp_eq_u32_e32 vcc, v156, v215
	v_cndmask_b32_e64 v157, v157, v215, s[22:23]
	s_nop 0
	v_cndmask_b32_e32 v156, v156, v158, vcc
	v_cndmask_b32_e32 v158, v158, v159, vcc
	v_cndmask_b32_e32 v159, v159, v160, vcc
	v_max_u32_dpp v215, v156, v156 row_ror:1 row_mask:0xf bank_mask:0xf bound_ctrl:1
	v_cndmask_b32_e32 v160, v160, v161, vcc
	v_cndmask_b32_e32 v161, v161, v206, vcc
	v_max_u32_dpp v215, v215, v215 row_ror:2 row_mask:0xf bank_mask:0xf bound_ctrl:1
	v_cndmask_b32_e32 v206, v206, v207, vcc
	v_cndmask_b32_e32 v207, v207, v213, vcc
	v_max_u32_dpp v215, v215, v215 row_ror:4 row_mask:0xf bank_mask:0xf bound_ctrl:1
	v_cndmask_b32_e64 v213, v213, 0, vcc
	s_nop 0
	v_max_u32_dpp v215, v215, v215 row_ror:8 row_mask:0xf bank_mask:0xf bound_ctrl:1
	v_cmp_eq_u32_e32 vcc, v156, v215
	v_cndmask_b32_e64 v157, v157, v215, s[24:25]
	s_nop 0
	v_cndmask_b32_e32 v156, v156, v158, vcc
	v_cndmask_b32_e32 v158, v158, v159, vcc
	v_cndmask_b32_e32 v159, v159, v160, vcc
	v_max_u32_dpp v215, v156, v156 row_ror:1 row_mask:0xf bank_mask:0xf bound_ctrl:1
	v_cndmask_b32_e32 v160, v160, v161, vcc
	v_cndmask_b32_e32 v161, v161, v206, vcc
	v_max_u32_dpp v215, v215, v215 row_ror:2 row_mask:0xf bank_mask:0xf bound_ctrl:1
	v_cndmask_b32_e32 v206, v206, v207, vcc
	v_cndmask_b32_e32 v207, v207, v213, vcc
	v_max_u32_dpp v215, v215, v215 row_ror:4 row_mask:0xf bank_mask:0xf bound_ctrl:1
	v_cndmask_b32_e64 v213, v213, 0, vcc
	s_nop 0
	v_max_u32_dpp v215, v215, v215 row_ror:8 row_mask:0xf bank_mask:0xf bound_ctrl:1
	v_cmp_eq_u32_e32 vcc, v156, v215
	v_cndmask_b32_e64 v157, v157, v215, s[26:27]
	s_nop 0
	v_cndmask_b32_e32 v156, v156, v158, vcc
	v_cndmask_b32_e32 v158, v158, v159, vcc
	v_cndmask_b32_e32 v159, v159, v160, vcc
	v_max_u32_dpp v215, v156, v156 row_ror:1 row_mask:0xf bank_mask:0xf bound_ctrl:1
	v_cndmask_b32_e32 v160, v160, v161, vcc
	v_cndmask_b32_e32 v161, v161, v206, vcc
	v_max_u32_dpp v215, v215, v215 row_ror:2 row_mask:0xf bank_mask:0xf bound_ctrl:1
	v_cndmask_b32_e32 v206, v206, v207, vcc
	v_cndmask_b32_e32 v207, v207, v213, vcc
	v_max_u32_dpp v215, v215, v215 row_ror:4 row_mask:0xf bank_mask:0xf bound_ctrl:1
	v_cndmask_b32_e64 v213, v213, 0, vcc
	s_nop 0
	v_max_u32_dpp v215, v215, v215 row_ror:8 row_mask:0xf bank_mask:0xf bound_ctrl:1
	v_cmp_eq_u32_e32 vcc, v156, v215
	v_cndmask_b32_e64 v157, v157, v215, s[28:29]
	s_nop 0
	v_cndmask_b32_e32 v156, v156, v158, vcc
	v_cndmask_b32_e32 v158, v158, v159, vcc
	v_cndmask_b32_e32 v159, v159, v160, vcc
	v_cndmask_b32_e32 v160, v160, v161, vcc
	v_cndmask_b32_e32 v161, v161, v206, vcc
	v_cndmask_b32_e32 v206, v206, v207, vcc
	v_cndmask_b32_e32 v207, v207, v213, vcc
	v_max_u32_dpp v213, v156, v156 row_ror:1 row_mask:0xf bank_mask:0xf bound_ctrl:1
	s_nop 1
	v_max_u32_dpp v213, v213, v213 row_ror:2 row_mask:0xf bank_mask:0xf bound_ctrl:1
	s_nop 1
	v_max_u32_dpp v213, v213, v213 row_ror:4 row_mask:0xf bank_mask:0xf bound_ctrl:1
	s_nop 1
	v_max_u32_dpp v213, v213, v213 row_ror:8 row_mask:0xf bank_mask:0xf bound_ctrl:1
	v_cmp_eq_u32_e32 vcc, v156, v213
	v_cndmask_b32_e64 v157, v157, v213, s[30:31]
	s_nop 0
	v_cndmask_b32_e32 v156, v156, v158, vcc
	v_cndmask_b32_e32 v158, v158, v159, vcc
	v_cndmask_b32_e32 v159, v159, v160, vcc
	v_cndmask_b32_e32 v160, v160, v161, vcc
	v_cndmask_b32_e32 v161, v161, v206, vcc
	v_cndmask_b32_e32 v206, v206, v207, vcc
	v_max_u32_dpp v207, v156, v156 row_ror:1 row_mask:0xf bank_mask:0xf bound_ctrl:1
	s_nop 1
	v_max_u32_dpp v207, v207, v207 row_ror:2 row_mask:0xf bank_mask:0xf bound_ctrl:1
	s_nop 1
	v_max_u32_dpp v207, v207, v207 row_ror:4 row_mask:0xf bank_mask:0xf bound_ctrl:1
	s_nop 1
	v_max_u32_dpp v207, v207, v207 row_ror:8 row_mask:0xf bank_mask:0xf bound_ctrl:1
	v_cmp_eq_u32_e32 vcc, v156, v207
	v_cndmask_b32_e64 v157, v157, v207, s[34:35]
	s_nop 0
	v_cndmask_b32_e32 v156, v156, v158, vcc
	v_cndmask_b32_e32 v158, v158, v159, vcc
	v_cndmask_b32_e32 v159, v159, v160, vcc
	v_cndmask_b32_e32 v160, v160, v161, vcc
	v_cndmask_b32_e32 v161, v161, v206, vcc
	v_max_u32_dpp v206, v156, v156 row_ror:1 row_mask:0xf bank_mask:0xf bound_ctrl:1
	s_nop 1
	v_max_u32_dpp v206, v206, v206 row_ror:2 row_mask:0xf bank_mask:0xf bound_ctrl:1
	s_nop 1
; __device__ __forceinline__ void peer_topk(const u32x4 (&scv)[4], const int lane, int (&eidx)[2], float (&gate)[2]) {
;     ...
;     for (int rd = 0; rd < 16; ++rd) {
;       const unsigned wk = rowmax_u(k[0]);
;       if (li == rd) keep = wk;
;       const bool win = (k[0] == wk);
;       k[0] = win ? k[1] : k[0]; k[1] = win ? k[2] : k[1]; k[2] = win ? k[3] : k[2]; k[3] = win ? k[4] : k[3];
;       k[4] = win ? k[5] : k[4]; k[5] = win ? k[6] : k[5]; k[6] = win ? k[7] : k[6]; k[7] = win ? 0u : k[7];
;     }
;     res[pp] = keep;
	v_max_u32_dpp v206, v206, v206 row_ror:4 row_mask:0xf bank_mask:0xf bound_ctrl:1
	s_nop 1
	v_max_u32_dpp v206, v206, v206 row_ror:8 row_mask:0xf bank_mask:0xf bound_ctrl:1
	v_cmp_eq_u32_e32 vcc, v156, v206
	v_cndmask_b32_e64 v157, v157, v206, s[36:37]
	s_nop 0
	v_cndmask_b32_e32 v156, v156, v158, vcc
	v_cndmask_b32_e32 v158, v158, v159, vcc
	v_cndmask_b32_e32 v159, v159, v160, vcc
	v_cndmask_b32_e32 v160, v160, v161, vcc
	v_max_u32_dpp v161, v156, v156 row_ror:1 row_mask:0xf bank_mask:0xf bound_ctrl:1
	s_nop 1
	v_max_u32_dpp v161, v161, v161 row_ror:2 row_mask:0xf bank_mask:0xf bound_ctrl:1
	s_nop 1
	v_max_u32_dpp v161, v161, v161 row_ror:4 row_mask:0xf bank_mask:0xf bound_ctrl:1
	s_nop 1
	v_max_u32_dpp v161, v161, v161 row_ror:8 row_mask:0xf bank_mask:0xf bound_ctrl:1
	v_cmp_eq_u32_e32 vcc, v156, v161
	v_cndmask_b32_e64 v157, v157, v161, s[38:39]
	s_nop 0
	v_cndmask_b32_e32 v156, v156, v158, vcc
	v_cndmask_b32_e32 v158, v158, v159, vcc
	v_cndmask_b32_e32 v159, v159, v160, vcc
	v_max_u32_dpp v160, v156, v156 row_ror:1 row_mask:0xf bank_mask:0xf bound_ctrl:1
	s_nop 1
	v_max_u32_dpp v160, v160, v160 row_ror:2 row_mask:0xf bank_mask:0xf bound_ctrl:1
	s_nop 1
	v_max_u32_dpp v160, v160, v160 row_ror:4 row_mask:0xf bank_mask:0xf bound_ctrl:1
	s_nop 1
	v_max_u32_dpp v160, v160, v160 row_ror:8 row_mask:0xf bank_mask:0xf bound_ctrl:1
	v_cmp_eq_u32_e32 vcc, v156, v160
	v_cndmask_b32_e64 v157, v157, v160, s[40:41]
	s_nop 0
	v_cndmask_b32_e32 v156, v156, v158, vcc
	v_cndmask_b32_e32 v158, v158, v159, vcc
	s_nop 0
	v_max_u32_dpp v159, v156, v156 row_ror:1 row_mask:0xf bank_mask:0xf bound_ctrl:1
	s_nop 1
	v_max_u32_dpp v159, v159, v159 row_ror:2 row_mask:0xf bank_mask:0xf bound_ctrl:1
	s_nop 1
	v_max_u32_dpp v159, v159, v159 row_ror:4 row_mask:0xf bank_mask:0xf bound_ctrl:1
	s_nop 1
	v_max_u32_dpp v159, v159, v159 row_ror:8 row_mask:0xf bank_mask:0xf bound_ctrl:1
	v_cmp_eq_u32_e32 vcc, v156, v159
	v_cndmask_b32_e64 v157, v157, v159, s[42:43]
	s_nop 0
	v_cndmask_b32_e32 v156, v156, v158, vcc
	s_nop 1
	v_max_u32_dpp v156, v156, v156 row_ror:1 row_mask:0xf bank_mask:0xf bound_ctrl:1
	s_nop 1
	v_max_u32_dpp v156, v156, v156 row_ror:2 row_mask:0xf bank_mask:0xf bound_ctrl:1
	s_nop 1
	v_max_u32_dpp v156, v156, v156 row_ror:4 row_mask:0xf bank_mask:0xf bound_ctrl:1
	s_nop 1
	v_max_u32_dpp v156, v156, v156 row_ror:8 row_mask:0xf bank_mask:0xf bound_ctrl:1
	v_cndmask_b32_e64 v156, v157, v156, s[44:45]
	v_max_u32_dpp v157, v181, v181 row_ror:1 row_mask:0xf bank_mask:0xf bound_ctrl:1
	s_nop 1
	v_max_u32_dpp v157, v157, v157 row_ror:2 row_mask:0xf bank_mask:0xf bound_ctrl:1
	s_nop 1
	v_max_u32_dpp v157, v157, v157 row_ror:4 row_mask:0xf bank_mask:0xf bound_ctrl:1
	s_nop 1
	v_max_u32_dpp v157, v157, v157 row_ror:8 row_mask:0xf bank_mask:0xf bound_ctrl:1
	v_cmp_eq_u32_e32 vcc, v181, v157
	v_cndmask_b32_e64 v158, 0, v157, s[12:13]
	s_nop 0
	v_cndmask_b32_e32 v157, v181, v183, vcc
	v_cndmask_b32_e32 v159, v183, v184, vcc
	v_cndmask_b32_e32 v160, v184, v185, vcc
	v_max_u32_dpp v216, v157, v157 row_ror:1 row_mask:0xf bank_mask:0xf bound_ctrl:1
	v_cndmask_b32_e32 v161, v185, v186, vcc
	v_cndmask_b32_e32 v206, v186, v187, vcc
	v_max_u32_dpp v216, v216, v216 row_ror:2 row_mask:0xf bank_mask:0xf bound_ctrl:1
	v_cndmask_b32_e32 v207, v187, v188, vcc
	v_cndmask_b32_e32 v213, v188, v182, vcc
	v_max_u32_dpp v216, v216, v216 row_ror:4 row_mask:0xf bank_mask:0xf bound_ctrl:1
	v_cndmask_b32_e64 v215, v182, 0, vcc
	s_nop 0
	v_max_u32_dpp v216, v216, v216 row_ror:8 row_mask:0xf bank_mask:0xf bound_ctrl:1
	v_cmp_eq_u32_e32 vcc, v157, v216
	v_cndmask_b32_e64 v158, v158, v216, s[14:15]
	s_nop 0
	v_cndmask_b32_e32 v157, v157, v159, vcc
	v_cndmask_b32_e32 v159, v159, v160, vcc
	v_cndmask_b32_e32 v160, v160, v161, vcc
	v_max_u32_dpp v216, v157, v157 row_ror:1 row_mask:0xf bank_mask:0xf bound_ctrl:1
	v_cndmask_b32_e32 v161, v161, v206, vcc
	v_cndmask_b32_e32 v206, v206, v207, vcc
	v_max_u32_dpp v216, v216, v216 row_ror:2 row_mask:0xf bank_mask:0xf bound_ctrl:1
	v_cndmask_b32_e32 v207, v207, v213, vcc
	v_cndmask_b32_e32 v213, v213, v215, vcc
	v_max_u32_dpp v216, v216, v216 row_ror:4 row_mask:0xf bank_mask:0xf bound_ctrl:1
	v_cndmask_b32_e64 v215, v215, 0, vcc
	s_nop 0
	v_max_u32_dpp v216, v216, v216 row_ror:8 row_mask:0xf bank_mask:0xf bound_ctrl:1
	v_cmp_eq_u32_e32 vcc, v157, v216
	v_cndmask_b32_e64 v158, v158, v216, s[16:17]
	s_nop 0
	v_cndmask_b32_e32 v157, v157, v159, vcc
	v_cndmask_b32_e32 v159, v159, v160, vcc
	v_cndmask_b32_e32 v160, v160, v161, vcc
	v_max_u32_dpp v216, v157, v157 row_ror:1 row_mask:0xf bank_mask:0xf bound_ctrl:1
	v_cndmask_b32_e32 v161, v161, v206, vcc
	v_cndmask_b32_e32 v206, v206, v207, vcc
	v_max_u32_dpp v216, v216, v216 row_ror:2 row_mask:0xf bank_mask:0xf bound_ctrl:1
	v_cndmask_b32_e32 v207, v207, v213, vcc
	v_cndmask_b32_e32 v213, v213, v215, vcc
	v_max_u32_dpp v216, v216, v216 row_ror:4 row_mask:0xf bank_mask:0xf bound_ctrl:1
	v_cndmask_b32_e64 v215, v215, 0, vcc
	s_nop 0
	v_max_u32_dpp v216, v216, v216 row_ror:8 row_mask:0xf bank_mask:0xf bound_ctrl:1
	v_cmp_eq_u32_e32 vcc, v157, v216
	v_cndmask_b32_e64 v158, v158, v216, s[18:19]
	s_nop 0
	v_cndmask_b32_e32 v157, v157, v159, vcc
	v_cndmask_b32_e32 v159, v159, v160, vcc
	v_cndmask_b32_e32 v160, v160, v161, vcc
	v_max_u32_dpp v216, v157, v157 row_ror:1 row_mask:0xf bank_mask:0xf bound_ctrl:1
	v_cndmask_b32_e32 v161, v161, v206, vcc
	v_cndmask_b32_e32 v206, v206, v207, vcc
	v_max_u32_dpp v216, v216, v216 row_ror:2 row_mask:0xf bank_mask:0xf bound_ctrl:1
	v_cndmask_b32_e32 v207, v207, v213, vcc
	v_cndmask_b32_e32 v213, v213, v215, vcc
	v_max_u32_dpp v216, v216, v216 row_ror:4 row_mask:0xf bank_mask:0xf bound_ctrl:1
; __device__ __forceinline__ void peer_topk(const u32x4 (&scv)[4], const int lane, int (&eidx)[2], float (&gate)[2]) {
;     ...
;     for (int rd = 0; rd < 16; ++rd) {
;       const unsigned wk = rowmax_u(k[0]);
;       if (li == rd) keep = wk;
;       const bool win = (k[0] == wk);
;       k[0] = win ? k[1] : k[0]; k[1] = win ? k[2] : k[1]; k[2] = win ? k[3] : k[2]; k[3] = win ? k[4] : k[3];
;       k[4] = win ? k[5] : k[4]; k[5] = win ? k[6] : k[5]; k[6] = win ? k[7] : k[6]; k[7] = win ? 0u : k[7];
;     }
;     res[pp] = keep;
	v_cndmask_b32_e64 v215, v215, 0, vcc
	s_nop 0
	v_max_u32_dpp v216, v216, v216 row_ror:8 row_mask:0xf bank_mask:0xf bound_ctrl:1
	v_cmp_eq_u32_e32 vcc, v157, v216
	v_cndmask_b32_e64 v158, v158, v216, s[20:21]
	s_nop 0
	v_cndmask_b32_e32 v157, v157, v159, vcc
	v_cndmask_b32_e32 v159, v159, v160, vcc
	v_cndmask_b32_e32 v160, v160, v161, vcc
	v_max_u32_dpp v216, v157, v157 row_ror:1 row_mask:0xf bank_mask:0xf bound_ctrl:1
	v_cndmask_b32_e32 v161, v161, v206, vcc
	v_cndmask_b32_e32 v206, v206, v207, vcc
	v_max_u32_dpp v216, v216, v216 row_ror:2 row_mask:0xf bank_mask:0xf bound_ctrl:1
	v_cndmask_b32_e32 v207, v207, v213, vcc
	v_cndmask_b32_e32 v213, v213, v215, vcc
	v_max_u32_dpp v216, v216, v216 row_ror:4 row_mask:0xf bank_mask:0xf bound_ctrl:1
	v_cndmask_b32_e64 v215, v215, 0, vcc
	s_nop 0
	v_max_u32_dpp v216, v216, v216 row_ror:8 row_mask:0xf bank_mask:0xf bound_ctrl:1
	v_cmp_eq_u32_e32 vcc, v157, v216
	v_cndmask_b32_e64 v158, v158, v216, s[22:23]
	s_nop 0
	v_cndmask_b32_e32 v157, v157, v159, vcc
	v_cndmask_b32_e32 v159, v159, v160, vcc
	v_cndmask_b32_e32 v160, v160, v161, vcc
	v_max_u32_dpp v216, v157, v157 row_ror:1 row_mask:0xf bank_mask:0xf bound_ctrl:1
	v_cndmask_b32_e32 v161, v161, v206, vcc
	v_cndmask_b32_e32 v206, v206, v207, vcc
	v_max_u32_dpp v216, v216, v216 row_ror:2 row_mask:0xf bank_mask:0xf bound_ctrl:1
	v_cndmask_b32_e32 v207, v207, v213, vcc
	v_cndmask_b32_e32 v213, v213, v215, vcc
	v_max_u32_dpp v216, v216, v216 row_ror:4 row_mask:0xf bank_mask:0xf bound_ctrl:1
	v_cndmask_b32_e64 v215, v215, 0, vcc
	s_nop 0
	v_max_u32_dpp v216, v216, v216 row_ror:8 row_mask:0xf bank_mask:0xf bound_ctrl:1
	v_cmp_eq_u32_e32 vcc, v157, v216
	v_cndmask_b32_e64 v158, v158, v216, s[24:25]
	s_nop 0
	v_cndmask_b32_e32 v157, v157, v159, vcc
	v_cndmask_b32_e32 v159, v159, v160, vcc
	v_cndmask_b32_e32 v160, v160, v161, vcc
	v_max_u32_dpp v216, v157, v157 row_ror:1 row_mask:0xf bank_mask:0xf bound_ctrl:1
	v_cndmask_b32_e32 v161, v161, v206, vcc
	v_cndmask_b32_e32 v206, v206, v207, vcc
	v_max_u32_dpp v216, v216, v216 row_ror:2 row_mask:0xf bank_mask:0xf bound_ctrl:1
	v_cndmask_b32_e32 v207, v207, v213, vcc
	v_cndmask_b32_e32 v213, v213, v215, vcc
	v_max_u32_dpp v216, v216, v216 row_ror:4 row_mask:0xf bank_mask:0xf bound_ctrl:1
	v_cndmask_b32_e64 v215, v215, 0, vcc
	s_nop 0
	v_max_u32_dpp v216, v216, v216 row_ror:8 row_mask:0xf bank_mask:0xf bound_ctrl:1
	v_cmp_eq_u32_e32 vcc, v157, v216
	v_cndmask_b32_e64 v158, v158, v216, s[26:27]
	s_nop 0
	v_cndmask_b32_e32 v157, v157, v159, vcc
	v_cndmask_b32_e32 v159, v159, v160, vcc
	v_cndmask_b32_e32 v160, v160, v161, vcc
	v_max_u32_dpp v216, v157, v157 row_ror:1 row_mask:0xf bank_mask:0xf bound_ctrl:1
	v_cndmask_b32_e32 v161, v161, v206, vcc
	v_cndmask_b32_e32 v206, v206, v207, vcc
	v_max_u32_dpp v216, v216, v216 row_ror:2 row_mask:0xf bank_mask:0xf bound_ctrl:1
	v_cndmask_b32_e32 v207, v207, v213, vcc
	v_cndmask_b32_e32 v213, v213, v215, vcc
	v_max_u32_dpp v216, v216, v216 row_ror:4 row_mask:0xf bank_mask:0xf bound_ctrl:1
	v_cndmask_b32_e64 v215, v215, 0, vcc
	s_nop 0
	v_max_u32_dpp v216, v216, v216 row_ror:8 row_mask:0xf bank_mask:0xf bound_ctrl:1
	v_cmp_eq_u32_e32 vcc, v157, v216
	v_cndmask_b32_e64 v158, v158, v216, s[28:29]
	s_nop 0
	v_cndmask_b32_e32 v157, v157, v159, vcc
	v_cndmask_b32_e32 v159, v159, v160, vcc
	v_cndmask_b32_e32 v160, v160, v161, vcc
	v_cndmask_b32_e32 v161, v161, v206, vcc
	v_cndmask_b32_e32 v206, v206, v207, vcc
	v_cndmask_b32_e32 v207, v207, v213, vcc
	v_cndmask_b32_e32 v213, v213, v215, vcc
	v_max_u32_dpp v215, v157, v157 row_ror:1 row_mask:0xf bank_mask:0xf bound_ctrl:1
	s_nop 1
	v_max_u32_dpp v215, v215, v215 row_ror:2 row_mask:0xf bank_mask:0xf bound_ctrl:1
	s_nop 1
	v_max_u32_dpp v215, v215, v215 row_ror:4 row_mask:0xf bank_mask:0xf bound_ctrl:1
	s_nop 1
	v_max_u32_dpp v215, v215, v215 row_ror:8 row_mask:0xf bank_mask:0xf bound_ctrl:1
	v_cmp_eq_u32_e32 vcc, v157, v215
	v_cndmask_b32_e64 v158, v158, v215, s[30:31]
	s_nop 0
	v_cndmask_b32_e32 v157, v157, v159, vcc
	v_cndmask_b32_e32 v159, v159, v160, vcc
	v_cndmask_b32_e32 v160, v160, v161, vcc
	v_cndmask_b32_e32 v161, v161, v206, vcc
	v_cndmask_b32_e32 v206, v206, v207, vcc
	v_cndmask_b32_e32 v207, v207, v213, vcc
	v_max_u32_dpp v213, v157, v157 row_ror:1 row_mask:0xf bank_mask:0xf bound_ctrl:1
	s_nop 1
	v_max_u32_dpp v213, v213, v213 row_ror:2 row_mask:0xf bank_mask:0xf bound_ctrl:1
	s_nop 1
	v_max_u32_dpp v213, v213, v213 row_ror:4 row_mask:0xf bank_mask:0xf bound_ctrl:1
	s_nop 1
	v_max_u32_dpp v213, v213, v213 row_ror:8 row_mask:0xf bank_mask:0xf bound_ctrl:1
	v_cmp_eq_u32_e32 vcc, v157, v213
	v_cndmask_b32_e64 v158, v158, v213, s[34:35]
	s_nop 0
	v_cndmask_b32_e32 v157, v157, v159, vcc
	v_cndmask_b32_e32 v159, v159, v160, vcc
	v_cndmask_b32_e32 v160, v160, v161, vcc
	v_cndmask_b32_e32 v161, v161, v206, vcc
	v_cndmask_b32_e32 v206, v206, v207, vcc
	v_max_u32_dpp v207, v157, v157 row_ror:1 row_mask:0xf bank_mask:0xf bound_ctrl:1
	s_nop 1
	v_max_u32_dpp v207, v207, v207 row_ror:2 row_mask:0xf bank_mask:0xf bound_ctrl:1
	s_nop 1
	v_max_u32_dpp v207, v207, v207 row_ror:4 row_mask:0xf bank_mask:0xf bound_ctrl:1
	s_nop 1
	v_max_u32_dpp v207, v207, v207 row_ror:8 row_mask:0xf bank_mask:0xf bound_ctrl:1
	v_cmp_eq_u32_e32 vcc, v157, v207
	v_cndmask_b32_e64 v158, v158, v207, s[36:37]
	s_nop 0
	v_cndmask_b32_e32 v157, v157, v159, vcc
	v_cndmask_b32_e32 v159, v159, v160, vcc
	v_cndmask_b32_e32 v160, v160, v161, vcc
	v_cndmask_b32_e32 v161, v161, v206, vcc
	v_max_u32_dpp v206, v157, v157 row_ror:1 row_mask:0xf bank_mask:0xf bound_ctrl:1
	s_nop 1
	v_max_u32_dpp v206, v206, v206 row_ror:2 row_mask:0xf bank_mask:0xf bound_ctrl:1
	s_nop 1
; __device__ __forceinline__ void peer_topk(const u32x4 (&scv)[4], const int lane, int (&eidx)[2], float (&gate)[2]) {
;     ...
;     for (int rd = 0; rd < 16; ++rd) {
;       const unsigned wk = rowmax_u(k[0]);
;       if (li == rd) keep = wk;
;       const bool win = (k[0] == wk);
;       k[0] = win ? k[1] : k[0]; k[1] = win ? k[2] : k[1]; k[2] = win ? k[3] : k[2]; k[3] = win ? k[4] : k[3];
;       k[4] = win ? k[5] : k[4]; k[5] = win ? k[6] : k[5]; k[6] = win ? k[7] : k[6]; k[7] = win ? 0u : k[7];
;     }
;     res[pp] = keep;
	v_max_u32_dpp v206, v206, v206 row_ror:4 row_mask:0xf bank_mask:0xf bound_ctrl:1
	s_nop 1
	v_max_u32_dpp v206, v206, v206 row_ror:8 row_mask:0xf bank_mask:0xf bound_ctrl:1
	v_cmp_eq_u32_e32 vcc, v157, v206
	v_cndmask_b32_e64 v158, v158, v206, s[38:39]
	s_nop 0
	v_cndmask_b32_e32 v157, v157, v159, vcc
	v_cndmask_b32_e32 v159, v159, v160, vcc
	v_cndmask_b32_e32 v160, v160, v161, vcc
	v_max_u32_dpp v161, v157, v157 row_ror:1 row_mask:0xf bank_mask:0xf bound_ctrl:1
	s_nop 1
	v_max_u32_dpp v161, v161, v161 row_ror:2 row_mask:0xf bank_mask:0xf bound_ctrl:1
	s_nop 1
	v_max_u32_dpp v161, v161, v161 row_ror:4 row_mask:0xf bank_mask:0xf bound_ctrl:1
	s_nop 1
	v_max_u32_dpp v161, v161, v161 row_ror:8 row_mask:0xf bank_mask:0xf bound_ctrl:1
	v_cmp_eq_u32_e32 vcc, v157, v161
	v_cndmask_b32_e64 v158, v158, v161, s[40:41]
	s_nop 0
	v_cndmask_b32_e32 v157, v157, v159, vcc
	v_cndmask_b32_e32 v159, v159, v160, vcc
	s_nop 0
	v_max_u32_dpp v160, v157, v157 row_ror:1 row_mask:0xf bank_mask:0xf bound_ctrl:1
	s_nop 1
	v_max_u32_dpp v160, v160, v160 row_ror:2 row_mask:0xf bank_mask:0xf bound_ctrl:1
	s_nop 1
	v_max_u32_dpp v160, v160, v160 row_ror:4 row_mask:0xf bank_mask:0xf bound_ctrl:1
	s_nop 1
	v_max_u32_dpp v160, v160, v160 row_ror:8 row_mask:0xf bank_mask:0xf bound_ctrl:1
	v_cmp_eq_u32_e32 vcc, v157, v160
	v_cndmask_b32_e64 v158, v158, v160, s[42:43]
	s_nop 0
	v_cndmask_b32_e32 v157, v157, v159, vcc
	s_nop 1
	v_max_u32_dpp v157, v157, v157 row_ror:1 row_mask:0xf bank_mask:0xf bound_ctrl:1
	s_nop 1
	v_max_u32_dpp v157, v157, v157 row_ror:2 row_mask:0xf bank_mask:0xf bound_ctrl:1
	s_nop 1
	v_max_u32_dpp v157, v157, v157 row_ror:4 row_mask:0xf bank_mask:0xf bound_ctrl:1
	s_nop 1
	v_max_u32_dpp v157, v157, v157 row_ror:8 row_mask:0xf bank_mask:0xf bound_ctrl:1
	v_cndmask_b32_e64 v158, v158, v157, s[44:45]
	s_nop 0
	v_max_u32_dpp v157, v189, v189 row_ror:1 row_mask:0xf bank_mask:0xf bound_ctrl:1
	s_nop 1
	v_max_u32_dpp v157, v157, v157 row_ror:2 row_mask:0xf bank_mask:0xf bound_ctrl:1
	s_nop 1
	v_max_u32_dpp v157, v157, v157 row_ror:4 row_mask:0xf bank_mask:0xf bound_ctrl:1
	s_nop 1
	v_max_u32_dpp v157, v157, v157 row_ror:8 row_mask:0xf bank_mask:0xf bound_ctrl:1
	v_cmp_eq_u32_e32 vcc, v189, v157
	v_cndmask_b32_e64 v159, 0, v157, s[12:13]
	s_nop 0
	v_cndmask_b32_e32 v157, v189, v191, vcc
	v_cndmask_b32_e32 v160, v191, v192, vcc
	v_cndmask_b32_e32 v161, v192, v193, vcc
	v_max_u32_dpp v217, v157, v157 row_ror:1 row_mask:0xf bank_mask:0xf bound_ctrl:1
	v_cndmask_b32_e32 v206, v193, v194, vcc
	v_cndmask_b32_e32 v207, v194, v195, vcc
	v_max_u32_dpp v217, v217, v217 row_ror:2 row_mask:0xf bank_mask:0xf bound_ctrl:1
	v_cndmask_b32_e32 v213, v195, v196, vcc
	v_cndmask_b32_e32 v215, v196, v190, vcc
	v_max_u32_dpp v217, v217, v217 row_ror:4 row_mask:0xf bank_mask:0xf bound_ctrl:1
	v_cndmask_b32_e64 v216, v190, 0, vcc
	s_nop 0
	v_max_u32_dpp v217, v217, v217 row_ror:8 row_mask:0xf bank_mask:0xf bound_ctrl:1
	v_cmp_eq_u32_e32 vcc, v157, v217
	v_cndmask_b32_e64 v159, v159, v217, s[14:15]
	s_nop 0
	v_cndmask_b32_e32 v157, v157, v160, vcc
	v_cndmask_b32_e32 v160, v160, v161, vcc
	v_cndmask_b32_e32 v161, v161, v206, vcc
	v_max_u32_dpp v217, v157, v157 row_ror:1 row_mask:0xf bank_mask:0xf bound_ctrl:1
	v_cndmask_b32_e32 v206, v206, v207, vcc
	v_cndmask_b32_e32 v207, v207, v213, vcc
	v_max_u32_dpp v217, v217, v217 row_ror:2 row_mask:0xf bank_mask:0xf bound_ctrl:1
	v_cndmask_b32_e32 v213, v213, v215, vcc
	v_cndmask_b32_e32 v215, v215, v216, vcc
	v_max_u32_dpp v217, v217, v217 row_ror:4 row_mask:0xf bank_mask:0xf bound_ctrl:1
	v_cndmask_b32_e64 v216, v216, 0, vcc
	s_nop 0
	v_max_u32_dpp v217, v217, v217 row_ror:8 row_mask:0xf bank_mask:0xf bound_ctrl:1
	v_cmp_eq_u32_e32 vcc, v157, v217
	v_cndmask_b32_e64 v159, v159, v217, s[16:17]
	s_nop 0
	v_cndmask_b32_e32 v157, v157, v160, vcc
	v_cndmask_b32_e32 v160, v160, v161, vcc
	v_cndmask_b32_e32 v161, v161, v206, vcc
	v_max_u32_dpp v217, v157, v157 row_ror:1 row_mask:0xf bank_mask:0xf bound_ctrl:1
	v_cndmask_b32_e32 v206, v206, v207, vcc
	v_cndmask_b32_e32 v207, v207, v213, vcc
	v_max_u32_dpp v217, v217, v217 row_ror:2 row_mask:0xf bank_mask:0xf bound_ctrl:1
	v_cndmask_b32_e32 v213, v213, v215, vcc
	v_cndmask_b32_e32 v215, v215, v216, vcc
	v_max_u32_dpp v217, v217, v217 row_ror:4 row_mask:0xf bank_mask:0xf bound_ctrl:1
	v_cndmask_b32_e64 v216, v216, 0, vcc
	s_nop 0
	v_max_u32_dpp v217, v217, v217 row_ror:8 row_mask:0xf bank_mask:0xf bound_ctrl:1
	v_cmp_eq_u32_e32 vcc, v157, v217
	v_cndmask_b32_e64 v159, v159, v217, s[18:19]
	s_nop 0
	v_cndmask_b32_e32 v157, v157, v160, vcc
	v_cndmask_b32_e32 v160, v160, v161, vcc
	v_cndmask_b32_e32 v161, v161, v206, vcc
	v_max_u32_dpp v217, v157, v157 row_ror:1 row_mask:0xf bank_mask:0xf bound_ctrl:1
	v_cndmask_b32_e32 v206, v206, v207, vcc
	v_cndmask_b32_e32 v207, v207, v213, vcc
	v_max_u32_dpp v217, v217, v217 row_ror:2 row_mask:0xf bank_mask:0xf bound_ctrl:1
	v_cndmask_b32_e32 v213, v213, v215, vcc
	v_cndmask_b32_e32 v215, v215, v216, vcc
	v_max_u32_dpp v217, v217, v217 row_ror:4 row_mask:0xf bank_mask:0xf bound_ctrl:1
	v_cndmask_b32_e64 v216, v216, 0, vcc
	s_nop 0
	v_max_u32_dpp v217, v217, v217 row_ror:8 row_mask:0xf bank_mask:0xf bound_ctrl:1
	v_cmp_eq_u32_e32 vcc, v157, v217
	v_cndmask_b32_e64 v159, v159, v217, s[20:21]
	s_nop 0
	v_cndmask_b32_e32 v157, v157, v160, vcc
	v_cndmask_b32_e32 v160, v160, v161, vcc
	v_cndmask_b32_e32 v161, v161, v206, vcc
	v_max_u32_dpp v217, v157, v157 row_ror:1 row_mask:0xf bank_mask:0xf bound_ctrl:1
	v_cndmask_b32_e32 v206, v206, v207, vcc
	v_cndmask_b32_e32 v207, v207, v213, vcc
	v_max_u32_dpp v217, v217, v217 row_ror:2 row_mask:0xf bank_mask:0xf bound_ctrl:1
; __device__ __forceinline__ void peer_topk(const u32x4 (&scv)[4], const int lane, int (&eidx)[2], float (&gate)[2]) {
;     ...
;     for (int rd = 0; rd < 16; ++rd) {
;       const unsigned wk = rowmax_u(k[0]);
;       if (li == rd) keep = wk;
;       const bool win = (k[0] == wk);
;       k[0] = win ? k[1] : k[0]; k[1] = win ? k[2] : k[1]; k[2] = win ? k[3] : k[2]; k[3] = win ? k[4] : k[3];
;       k[4] = win ? k[5] : k[4]; k[5] = win ? k[6] : k[5]; k[6] = win ? k[7] : k[6]; k[7] = win ? 0u : k[7];
;     }
;     res[pp] = keep;
	v_cndmask_b32_e32 v213, v213, v215, vcc
	v_cndmask_b32_e32 v215, v215, v216, vcc
	v_max_u32_dpp v217, v217, v217 row_ror:4 row_mask:0xf bank_mask:0xf bound_ctrl:1
	v_cndmask_b32_e64 v216, v216, 0, vcc
	s_nop 0
	v_max_u32_dpp v217, v217, v217 row_ror:8 row_mask:0xf bank_mask:0xf bound_ctrl:1
	v_cmp_eq_u32_e32 vcc, v157, v217
	v_cndmask_b32_e64 v159, v159, v217, s[22:23]
	s_nop 0
	v_cndmask_b32_e32 v157, v157, v160, vcc
	v_cndmask_b32_e32 v160, v160, v161, vcc
	v_cndmask_b32_e32 v161, v161, v206, vcc
	v_max_u32_dpp v217, v157, v157 row_ror:1 row_mask:0xf bank_mask:0xf bound_ctrl:1
	v_cndmask_b32_e32 v206, v206, v207, vcc
	v_cndmask_b32_e32 v207, v207, v213, vcc
	v_max_u32_dpp v217, v217, v217 row_ror:2 row_mask:0xf bank_mask:0xf bound_ctrl:1
	v_cndmask_b32_e32 v213, v213, v215, vcc
	v_cndmask_b32_e32 v215, v215, v216, vcc
	v_max_u32_dpp v217, v217, v217 row_ror:4 row_mask:0xf bank_mask:0xf bound_ctrl:1
	v_cndmask_b32_e64 v216, v216, 0, vcc
	s_nop 0
	v_max_u32_dpp v217, v217, v217 row_ror:8 row_mask:0xf bank_mask:0xf bound_ctrl:1
	v_cmp_eq_u32_e32 vcc, v157, v217
	v_cndmask_b32_e64 v159, v159, v217, s[24:25]
	s_nop 0
	v_cndmask_b32_e32 v157, v157, v160, vcc
	v_cndmask_b32_e32 v160, v160, v161, vcc
	v_cndmask_b32_e32 v161, v161, v206, vcc
	v_max_u32_dpp v217, v157, v157 row_ror:1 row_mask:0xf bank_mask:0xf bound_ctrl:1
	v_cndmask_b32_e32 v206, v206, v207, vcc
	v_cndmask_b32_e32 v207, v207, v213, vcc
	v_max_u32_dpp v217, v217, v217 row_ror:2 row_mask:0xf bank_mask:0xf bound_ctrl:1
	v_cndmask_b32_e32 v213, v213, v215, vcc
	v_cndmask_b32_e32 v215, v215, v216, vcc
	v_max_u32_dpp v217, v217, v217 row_ror:4 row_mask:0xf bank_mask:0xf bound_ctrl:1
	v_cndmask_b32_e64 v216, v216, 0, vcc
	s_nop 0
	v_max_u32_dpp v217, v217, v217 row_ror:8 row_mask:0xf bank_mask:0xf bound_ctrl:1
	v_cmp_eq_u32_e32 vcc, v157, v217
	v_cndmask_b32_e64 v159, v159, v217, s[26:27]
	s_nop 0
	v_cndmask_b32_e32 v157, v157, v160, vcc
	v_cndmask_b32_e32 v160, v160, v161, vcc
	v_cndmask_b32_e32 v161, v161, v206, vcc
	v_max_u32_dpp v217, v157, v157 row_ror:1 row_mask:0xf bank_mask:0xf bound_ctrl:1
	v_cndmask_b32_e32 v206, v206, v207, vcc
	v_cndmask_b32_e32 v207, v207, v213, vcc
	v_max_u32_dpp v217, v217, v217 row_ror:2 row_mask:0xf bank_mask:0xf bound_ctrl:1
	v_cndmask_b32_e32 v213, v213, v215, vcc
	v_cndmask_b32_e32 v215, v215, v216, vcc
	v_max_u32_dpp v217, v217, v217 row_ror:4 row_mask:0xf bank_mask:0xf bound_ctrl:1
	v_cndmask_b32_e64 v216, v216, 0, vcc
	s_nop 0
	v_max_u32_dpp v217, v217, v217 row_ror:8 row_mask:0xf bank_mask:0xf bound_ctrl:1
	v_cmp_eq_u32_e32 vcc, v157, v217
	v_cndmask_b32_e64 v159, v159, v217, s[28:29]
	s_nop 0
	v_cndmask_b32_e32 v157, v157, v160, vcc
	v_cndmask_b32_e32 v160, v160, v161, vcc
	v_cndmask_b32_e32 v161, v161, v206, vcc
	v_cndmask_b32_e32 v206, v206, v207, vcc
	v_cndmask_b32_e32 v207, v207, v213, vcc
	v_cndmask_b32_e32 v213, v213, v215, vcc
	v_cndmask_b32_e32 v215, v215, v216, vcc
	v_max_u32_dpp v216, v157, v157 row_ror:1 row_mask:0xf bank_mask:0xf bound_ctrl:1
	s_nop 1
	v_max_u32_dpp v216, v216, v216 row_ror:2 row_mask:0xf bank_mask:0xf bound_ctrl:1
	s_nop 1
	v_max_u32_dpp v216, v216, v216 row_ror:4 row_mask:0xf bank_mask:0xf bound_ctrl:1
	s_nop 1
	v_max_u32_dpp v216, v216, v216 row_ror:8 row_mask:0xf bank_mask:0xf bound_ctrl:1
	v_cmp_eq_u32_e32 vcc, v157, v216
	v_cndmask_b32_e64 v159, v159, v216, s[30:31]
	s_nop 0
	v_cndmask_b32_e32 v157, v157, v160, vcc
	v_cndmask_b32_e32 v160, v160, v161, vcc
	v_cndmask_b32_e32 v161, v161, v206, vcc
	v_cndmask_b32_e32 v206, v206, v207, vcc
	v_cndmask_b32_e32 v207, v207, v213, vcc
	v_cndmask_b32_e32 v213, v213, v215, vcc
	v_max_u32_dpp v215, v157, v157 row_ror:1 row_mask:0xf bank_mask:0xf bound_ctrl:1
	s_nop 1
	v_max_u32_dpp v215, v215, v215 row_ror:2 row_mask:0xf bank_mask:0xf bound_ctrl:1
	s_nop 1
	v_max_u32_dpp v215, v215, v215 row_ror:4 row_mask:0xf bank_mask:0xf bound_ctrl:1
	s_nop 1
	v_max_u32_dpp v215, v215, v215 row_ror:8 row_mask:0xf bank_mask:0xf bound_ctrl:1
	v_cmp_eq_u32_e32 vcc, v157, v215
	v_cndmask_b32_e64 v159, v159, v215, s[34:35]
	s_nop 0
	v_cndmask_b32_e32 v157, v157, v160, vcc
	v_cndmask_b32_e32 v160, v160, v161, vcc
	v_cndmask_b32_e32 v161, v161, v206, vcc
	v_cndmask_b32_e32 v206, v206, v207, vcc
	v_cndmask_b32_e32 v207, v207, v213, vcc
	v_max_u32_dpp v213, v157, v157 row_ror:1 row_mask:0xf bank_mask:0xf bound_ctrl:1
	s_nop 1
	v_max_u32_dpp v213, v213, v213 row_ror:2 row_mask:0xf bank_mask:0xf bound_ctrl:1
	s_nop 1
	v_max_u32_dpp v213, v213, v213 row_ror:4 row_mask:0xf bank_mask:0xf bound_ctrl:1
	s_nop 1
	v_max_u32_dpp v213, v213, v213 row_ror:8 row_mask:0xf bank_mask:0xf bound_ctrl:1
	v_cmp_eq_u32_e32 vcc, v157, v213
	v_cndmask_b32_e64 v159, v159, v213, s[36:37]
	s_nop 0
	v_cndmask_b32_e32 v157, v157, v160, vcc
	v_cndmask_b32_e32 v160, v160, v161, vcc
	v_cndmask_b32_e32 v161, v161, v206, vcc
	v_cndmask_b32_e32 v206, v206, v207, vcc
	v_max_u32_dpp v207, v157, v157 row_ror:1 row_mask:0xf bank_mask:0xf bound_ctrl:1
	s_nop 1
	v_max_u32_dpp v207, v207, v207 row_ror:2 row_mask:0xf bank_mask:0xf bound_ctrl:1
	s_nop 1
	v_max_u32_dpp v207, v207, v207 row_ror:4 row_mask:0xf bank_mask:0xf bound_ctrl:1
	s_nop 1
	v_max_u32_dpp v207, v207, v207 row_ror:8 row_mask:0xf bank_mask:0xf bound_ctrl:1
	v_cmp_eq_u32_e32 vcc, v157, v207
	v_cndmask_b32_e64 v159, v159, v207, s[38:39]
	s_nop 0
	v_cndmask_b32_e32 v157, v157, v160, vcc
	v_cndmask_b32_e32 v160, v160, v161, vcc
	v_cndmask_b32_e32 v161, v161, v206, vcc
	v_max_u32_dpp v206, v157, v157 row_ror:1 row_mask:0xf bank_mask:0xf bound_ctrl:1
	s_nop 1
	v_max_u32_dpp v206, v206, v206 row_ror:2 row_mask:0xf bank_mask:0xf bound_ctrl:1
	s_nop 1
; __device__ __forceinline__ void peer_topk(const u32x4 (&scv)[4], const int lane, int (&eidx)[2], float (&gate)[2]) {
;     ...
;     for (int rd = 0; rd < 16; ++rd) {
;       const unsigned wk = rowmax_u(k[0]);
;       if (li == rd) keep = wk;
;       const bool win = (k[0] == wk);
;       k[0] = win ? k[1] : k[0]; k[1] = win ? k[2] : k[1]; k[2] = win ? k[3] : k[2]; k[3] = win ? k[4] : k[3];
;       k[4] = win ? k[5] : k[4]; k[5] = win ? k[6] : k[5]; k[6] = win ? k[7] : k[6]; k[7] = win ? 0u : k[7];
;     }
;     res[pp] = keep;
	v_max_u32_dpp v206, v206, v206 row_ror:4 row_mask:0xf bank_mask:0xf bound_ctrl:1
	s_nop 1
	v_max_u32_dpp v206, v206, v206 row_ror:8 row_mask:0xf bank_mask:0xf bound_ctrl:1
	v_cmp_eq_u32_e32 vcc, v157, v206
	v_cndmask_b32_e64 v159, v159, v206, s[40:41]
	s_nop 0
	v_cndmask_b32_e32 v157, v157, v160, vcc
	v_cndmask_b32_e32 v160, v160, v161, vcc
	s_nop 0
	v_max_u32_dpp v161, v157, v157 row_ror:1 row_mask:0xf bank_mask:0xf bound_ctrl:1
	s_nop 1
	v_max_u32_dpp v161, v161, v161 row_ror:2 row_mask:0xf bank_mask:0xf bound_ctrl:1
	s_nop 1
	v_max_u32_dpp v161, v161, v161 row_ror:4 row_mask:0xf bank_mask:0xf bound_ctrl:1
	s_nop 1
	v_max_u32_dpp v161, v161, v161 row_ror:8 row_mask:0xf bank_mask:0xf bound_ctrl:1
	v_cmp_eq_u32_e32 vcc, v157, v161
	v_cndmask_b32_e64 v159, v159, v161, s[42:43]
	s_nop 0
	v_cndmask_b32_e32 v157, v157, v160, vcc
	s_nop 1
	v_max_u32_dpp v157, v157, v157 row_ror:1 row_mask:0xf bank_mask:0xf bound_ctrl:1
	s_nop 1
	v_max_u32_dpp v157, v157, v157 row_ror:2 row_mask:0xf bank_mask:0xf bound_ctrl:1
	s_nop 1
	v_max_u32_dpp v157, v157, v157 row_ror:4 row_mask:0xf bank_mask:0xf bound_ctrl:1
	s_nop 1
	v_max_u32_dpp v157, v157, v157 row_ror:8 row_mask:0xf bank_mask:0xf bound_ctrl:1
	v_cndmask_b32_e64 v157, v159, v157, s[44:45]
	v_max_u32_dpp v159, v197, v197 row_ror:1 row_mask:0xf bank_mask:0xf bound_ctrl:1
	s_nop 1
	v_max_u32_dpp v159, v159, v159 row_ror:2 row_mask:0xf bank_mask:0xf bound_ctrl:1
	s_nop 1
	v_max_u32_dpp v159, v159, v159 row_ror:4 row_mask:0xf bank_mask:0xf bound_ctrl:1
	s_nop 1
	v_max_u32_dpp v159, v159, v159 row_ror:8 row_mask:0xf bank_mask:0xf bound_ctrl:1
	v_cmp_eq_u32_e32 vcc, v197, v159
	v_cndmask_b32_e64 v160, 0, v159, s[12:13]
	s_nop 0
	v_cndmask_b32_e32 v159, v197, v199, vcc
	v_cndmask_b32_e32 v161, v199, v200, vcc
	v_cndmask_b32_e32 v206, v200, v201, vcc
	v_max_u32_dpp v218, v159, v159 row_ror:1 row_mask:0xf bank_mask:0xf bound_ctrl:1
	v_cndmask_b32_e32 v207, v201, v202, vcc
	v_cndmask_b32_e32 v213, v202, v203, vcc
	v_max_u32_dpp v218, v218, v218 row_ror:2 row_mask:0xf bank_mask:0xf bound_ctrl:1
	v_cndmask_b32_e32 v215, v203, v204, vcc
	v_cndmask_b32_e32 v216, v204, v198, vcc
	v_max_u32_dpp v218, v218, v218 row_ror:4 row_mask:0xf bank_mask:0xf bound_ctrl:1
	v_cndmask_b32_e64 v217, v198, 0, vcc
	s_nop 0
	v_max_u32_dpp v218, v218, v218 row_ror:8 row_mask:0xf bank_mask:0xf bound_ctrl:1
	v_cmp_eq_u32_e32 vcc, v159, v218
	v_cndmask_b32_e64 v160, v160, v218, s[14:15]
	s_nop 0
	v_cndmask_b32_e32 v159, v159, v161, vcc
	v_cndmask_b32_e32 v161, v161, v206, vcc
	v_cndmask_b32_e32 v206, v206, v207, vcc
	v_max_u32_dpp v218, v159, v159 row_ror:1 row_mask:0xf bank_mask:0xf bound_ctrl:1
	v_cndmask_b32_e32 v207, v207, v213, vcc
	v_cndmask_b32_e32 v213, v213, v215, vcc
	v_max_u32_dpp v218, v218, v218 row_ror:2 row_mask:0xf bank_mask:0xf bound_ctrl:1
	v_cndmask_b32_e32 v215, v215, v216, vcc
	v_cndmask_b32_e32 v216, v216, v217, vcc
	v_max_u32_dpp v218, v218, v218 row_ror:4 row_mask:0xf bank_mask:0xf bound_ctrl:1
	v_cndmask_b32_e64 v217, v217, 0, vcc
	s_nop 0
	v_max_u32_dpp v218, v218, v218 row_ror:8 row_mask:0xf bank_mask:0xf bound_ctrl:1
	v_cmp_eq_u32_e32 vcc, v159, v218
	v_cndmask_b32_e64 v160, v160, v218, s[16:17]
	s_nop 0
	v_cndmask_b32_e32 v159, v159, v161, vcc
	v_cndmask_b32_e32 v161, v161, v206, vcc
	v_cndmask_b32_e32 v206, v206, v207, vcc
	v_max_u32_dpp v218, v159, v159 row_ror:1 row_mask:0xf bank_mask:0xf bound_ctrl:1
	v_cndmask_b32_e32 v207, v207, v213, vcc
	v_cndmask_b32_e32 v213, v213, v215, vcc
	v_max_u32_dpp v218, v218, v218 row_ror:2 row_mask:0xf bank_mask:0xf bound_ctrl:1
	v_cndmask_b32_e32 v215, v215, v216, vcc
	v_cndmask_b32_e32 v216, v216, v217, vcc
	v_max_u32_dpp v218, v218, v218 row_ror:4 row_mask:0xf bank_mask:0xf bound_ctrl:1
	v_cndmask_b32_e64 v217, v217, 0, vcc
	s_nop 0
	v_max_u32_dpp v218, v218, v218 row_ror:8 row_mask:0xf bank_mask:0xf bound_ctrl:1
	v_cmp_eq_u32_e32 vcc, v159, v218
	v_cndmask_b32_e64 v160, v160, v218, s[18:19]
	s_nop 0
	v_cndmask_b32_e32 v159, v159, v161, vcc
	v_cndmask_b32_e32 v161, v161, v206, vcc
	v_cndmask_b32_e32 v206, v206, v207, vcc
	v_max_u32_dpp v218, v159, v159 row_ror:1 row_mask:0xf bank_mask:0xf bound_ctrl:1
	v_cndmask_b32_e32 v207, v207, v213, vcc
	v_cndmask_b32_e32 v213, v213, v215, vcc
	v_max_u32_dpp v218, v218, v218 row_ror:2 row_mask:0xf bank_mask:0xf bound_ctrl:1
	v_cndmask_b32_e32 v215, v215, v216, vcc
	v_cndmask_b32_e32 v216, v216, v217, vcc
	v_max_u32_dpp v218, v218, v218 row_ror:4 row_mask:0xf bank_mask:0xf bound_ctrl:1
	v_cndmask_b32_e64 v217, v217, 0, vcc
	s_nop 0
	v_max_u32_dpp v218, v218, v218 row_ror:8 row_mask:0xf bank_mask:0xf bound_ctrl:1
	v_cmp_eq_u32_e32 vcc, v159, v218
	v_cndmask_b32_e64 v160, v160, v218, s[20:21]
	s_nop 0
	v_cndmask_b32_e32 v159, v159, v161, vcc
	v_cndmask_b32_e32 v161, v161, v206, vcc
	v_cndmask_b32_e32 v206, v206, v207, vcc
	v_max_u32_dpp v218, v159, v159 row_ror:1 row_mask:0xf bank_mask:0xf bound_ctrl:1
	v_cndmask_b32_e32 v207, v207, v213, vcc
	v_cndmask_b32_e32 v213, v213, v215, vcc
	v_max_u32_dpp v218, v218, v218 row_ror:2 row_mask:0xf bank_mask:0xf bound_ctrl:1
	v_cndmask_b32_e32 v215, v215, v216, vcc
	v_cndmask_b32_e32 v216, v216, v217, vcc
	v_max_u32_dpp v218, v218, v218 row_ror:4 row_mask:0xf bank_mask:0xf bound_ctrl:1
	v_cndmask_b32_e64 v217, v217, 0, vcc
	s_nop 0
	v_max_u32_dpp v218, v218, v218 row_ror:8 row_mask:0xf bank_mask:0xf bound_ctrl:1
	v_cmp_eq_u32_e32 vcc, v159, v218
	v_cndmask_b32_e64 v160, v160, v218, s[22:23]
	s_nop 0
	v_cndmask_b32_e32 v159, v159, v161, vcc
	v_cndmask_b32_e32 v161, v161, v206, vcc
	v_cndmask_b32_e32 v206, v206, v207, vcc
	v_max_u32_dpp v218, v159, v159 row_ror:1 row_mask:0xf bank_mask:0xf bound_ctrl:1
; __device__ __forceinline__ void peer_topk(const u32x4 (&scv)[4], const int lane, int (&eidx)[2], float (&gate)[2]) {
;     ...
;     for (int rd = 0; rd < 16; ++rd) {
;       const unsigned wk = rowmax_u(k[0]);
;       if (li == rd) keep = wk;
;       const bool win = (k[0] == wk);
;       k[0] = win ? k[1] : k[0]; k[1] = win ? k[2] : k[1]; k[2] = win ? k[3] : k[2]; k[3] = win ? k[4] : k[3];
;       k[4] = win ? k[5] : k[4]; k[5] = win ? k[6] : k[5]; k[6] = win ? k[7] : k[6]; k[7] = win ? 0u : k[7];
;     }
;     res[pp] = keep;
;   }
; #pragma unroll
;   for (int hp2 = 0; hp2 < 2; ++hp2) {
;     const unsigned k1 = res[hp2 * 2], k2 = res[hp2 * 2 + 1];
;     const float s1 = f_deord(k1 & ~0x7Fu), s2 = f_deord(k2 & ~0x7Fu);
;     const int i1 = 127 - (int)(k1 & 0x7Fu), i2 = 127 - (int)(k2 & 0x7Fu);
;     int ptr = 0;
;     unsigned keep = 0;
;     float s2p = __uint_as_float((unsigned)__builtin_amdgcn_ds_bpermute((rbase + 0) * 4, (int)__float_as_uint(s2)));
;     unsigned hk = (f_ord(s1 + s2p) & ~0xFFu) | (unsigned)(255 - (li * 16 + 0));
	v_cndmask_b32_e32 v207, v207, v213, vcc
	v_cndmask_b32_e32 v213, v213, v215, vcc
	v_max_u32_dpp v218, v218, v218 row_ror:2 row_mask:0xf bank_mask:0xf bound_ctrl:1
	v_cndmask_b32_e32 v215, v215, v216, vcc
	v_cndmask_b32_e32 v216, v216, v217, vcc
	v_max_u32_dpp v218, v218, v218 row_ror:4 row_mask:0xf bank_mask:0xf bound_ctrl:1
	v_cndmask_b32_e64 v217, v217, 0, vcc
	s_nop 0
	v_max_u32_dpp v218, v218, v218 row_ror:8 row_mask:0xf bank_mask:0xf bound_ctrl:1
	v_cmp_eq_u32_e32 vcc, v159, v218
	v_cndmask_b32_e64 v160, v160, v218, s[24:25]
	s_nop 0
	v_cndmask_b32_e32 v159, v159, v161, vcc
	v_cndmask_b32_e32 v161, v161, v206, vcc
	v_cndmask_b32_e32 v206, v206, v207, vcc
	v_max_u32_dpp v218, v159, v159 row_ror:1 row_mask:0xf bank_mask:0xf bound_ctrl:1
	v_cndmask_b32_e32 v207, v207, v213, vcc
	v_cndmask_b32_e32 v213, v213, v215, vcc
	v_max_u32_dpp v218, v218, v218 row_ror:2 row_mask:0xf bank_mask:0xf bound_ctrl:1
	v_cndmask_b32_e32 v215, v215, v216, vcc
	v_cndmask_b32_e32 v216, v216, v217, vcc
	v_max_u32_dpp v218, v218, v218 row_ror:4 row_mask:0xf bank_mask:0xf bound_ctrl:1
	v_cndmask_b32_e64 v217, v217, 0, vcc
	s_nop 0
	v_max_u32_dpp v218, v218, v218 row_ror:8 row_mask:0xf bank_mask:0xf bound_ctrl:1
	v_cmp_eq_u32_e32 vcc, v159, v218
	v_cndmask_b32_e64 v160, v160, v218, s[26:27]
	s_nop 0
	v_cndmask_b32_e32 v159, v159, v161, vcc
	v_cndmask_b32_e32 v161, v161, v206, vcc
	v_cndmask_b32_e32 v206, v206, v207, vcc
	v_max_u32_dpp v218, v159, v159 row_ror:1 row_mask:0xf bank_mask:0xf bound_ctrl:1
	v_cndmask_b32_e32 v207, v207, v213, vcc
	v_cndmask_b32_e32 v213, v213, v215, vcc
	v_max_u32_dpp v218, v218, v218 row_ror:2 row_mask:0xf bank_mask:0xf bound_ctrl:1
	v_cndmask_b32_e32 v215, v215, v216, vcc
	v_cndmask_b32_e32 v216, v216, v217, vcc
	v_max_u32_dpp v218, v218, v218 row_ror:4 row_mask:0xf bank_mask:0xf bound_ctrl:1
	v_cndmask_b32_e64 v217, v217, 0, vcc
	s_nop 0
	v_max_u32_dpp v218, v218, v218 row_ror:8 row_mask:0xf bank_mask:0xf bound_ctrl:1
	v_cmp_eq_u32_e32 vcc, v159, v218
	v_cndmask_b32_e64 v160, v160, v218, s[28:29]
	s_nop 0
	v_cndmask_b32_e32 v159, v159, v161, vcc
	v_cndmask_b32_e32 v161, v161, v206, vcc
	v_cndmask_b32_e32 v206, v206, v207, vcc
	v_cndmask_b32_e32 v207, v207, v213, vcc
	v_cndmask_b32_e32 v213, v213, v215, vcc
	v_cndmask_b32_e32 v215, v215, v216, vcc
	v_cndmask_b32_e32 v216, v216, v217, vcc
	v_max_u32_dpp v217, v159, v159 row_ror:1 row_mask:0xf bank_mask:0xf bound_ctrl:1
	s_nop 1
	v_max_u32_dpp v217, v217, v217 row_ror:2 row_mask:0xf bank_mask:0xf bound_ctrl:1
	s_nop 1
	v_max_u32_dpp v217, v217, v217 row_ror:4 row_mask:0xf bank_mask:0xf bound_ctrl:1
	s_nop 1
	v_max_u32_dpp v217, v217, v217 row_ror:8 row_mask:0xf bank_mask:0xf bound_ctrl:1
	v_cmp_eq_u32_e32 vcc, v159, v217
	v_cndmask_b32_e64 v160, v160, v217, s[30:31]
	s_nop 0
	v_cndmask_b32_e32 v159, v159, v161, vcc
	v_cndmask_b32_e32 v161, v161, v206, vcc
	v_cndmask_b32_e32 v206, v206, v207, vcc
	v_cndmask_b32_e32 v207, v207, v213, vcc
	v_cndmask_b32_e32 v213, v213, v215, vcc
	v_cndmask_b32_e32 v215, v215, v216, vcc
	v_max_u32_dpp v216, v159, v159 row_ror:1 row_mask:0xf bank_mask:0xf bound_ctrl:1
	s_nop 1
	v_max_u32_dpp v216, v216, v216 row_ror:2 row_mask:0xf bank_mask:0xf bound_ctrl:1
	s_nop 1
	v_max_u32_dpp v216, v216, v216 row_ror:4 row_mask:0xf bank_mask:0xf bound_ctrl:1
	s_nop 1
	v_max_u32_dpp v216, v216, v216 row_ror:8 row_mask:0xf bank_mask:0xf bound_ctrl:1
	v_cmp_eq_u32_e32 vcc, v159, v216
	v_cndmask_b32_e64 v160, v160, v216, s[34:35]
	s_nop 0
	v_cndmask_b32_e32 v159, v159, v161, vcc
	v_cndmask_b32_e32 v161, v161, v206, vcc
	v_cndmask_b32_e32 v206, v206, v207, vcc
	v_cndmask_b32_e32 v207, v207, v213, vcc
	v_cndmask_b32_e32 v213, v213, v215, vcc
	v_max_u32_dpp v215, v159, v159 row_ror:1 row_mask:0xf bank_mask:0xf bound_ctrl:1
	s_nop 1
	v_max_u32_dpp v215, v215, v215 row_ror:2 row_mask:0xf bank_mask:0xf bound_ctrl:1
	s_nop 1
	v_max_u32_dpp v215, v215, v215 row_ror:4 row_mask:0xf bank_mask:0xf bound_ctrl:1
	s_nop 1
	v_max_u32_dpp v215, v215, v215 row_ror:8 row_mask:0xf bank_mask:0xf bound_ctrl:1
	v_cmp_eq_u32_e32 vcc, v159, v215
	v_cndmask_b32_e64 v160, v160, v215, s[36:37]
	s_nop 0
	v_cndmask_b32_e32 v159, v159, v161, vcc
	v_cndmask_b32_e32 v161, v161, v206, vcc
	v_cndmask_b32_e32 v206, v206, v207, vcc
	v_cndmask_b32_e32 v207, v207, v213, vcc
	v_max_u32_dpp v213, v159, v159 row_ror:1 row_mask:0xf bank_mask:0xf bound_ctrl:1
	s_nop 1
	v_max_u32_dpp v213, v213, v213 row_ror:2 row_mask:0xf bank_mask:0xf bound_ctrl:1
	s_nop 1
	v_max_u32_dpp v213, v213, v213 row_ror:4 row_mask:0xf bank_mask:0xf bound_ctrl:1
	s_nop 1
	v_max_u32_dpp v213, v213, v213 row_ror:8 row_mask:0xf bank_mask:0xf bound_ctrl:1
	v_cmp_eq_u32_e32 vcc, v159, v213
	v_cndmask_b32_e64 v160, v160, v213, s[38:39]
	s_nop 0
	v_cndmask_b32_e32 v159, v159, v161, vcc
	v_cndmask_b32_e32 v161, v161, v206, vcc
	v_cndmask_b32_e32 v206, v206, v207, vcc
	v_max_u32_dpp v207, v159, v159 row_ror:1 row_mask:0xf bank_mask:0xf bound_ctrl:1
	s_nop 1
	v_max_u32_dpp v207, v207, v207 row_ror:2 row_mask:0xf bank_mask:0xf bound_ctrl:1
	s_nop 1
	v_max_u32_dpp v207, v207, v207 row_ror:4 row_mask:0xf bank_mask:0xf bound_ctrl:1
	s_nop 1
	v_max_u32_dpp v207, v207, v207 row_ror:8 row_mask:0xf bank_mask:0xf bound_ctrl:1
	v_cmp_eq_u32_e32 vcc, v159, v207
	v_cndmask_b32_e64 v160, v160, v207, s[40:41]
	s_nop 0
	v_cndmask_b32_e32 v159, v159, v161, vcc
	v_cndmask_b32_e32 v161, v161, v206, vcc
	s_nop 0
	v_max_u32_dpp v206, v159, v159 row_ror:1 row_mask:0xf bank_mask:0xf bound_ctrl:1
	s_nop 1
	v_max_u32_dpp v206, v206, v206 row_ror:2 row_mask:0xf bank_mask:0xf bound_ctrl:1
	s_nop 1
	v_max_u32_dpp v206, v206, v206 row_ror:4 row_mask:0xf bank_mask:0xf bound_ctrl:1
	s_nop 1
	v_max_u32_dpp v206, v206, v206 row_ror:8 row_mask:0xf bank_mask:0xf bound_ctrl:1
	v_cmp_eq_u32_e32 vcc, v159, v206
	v_cndmask_b32_e64 v160, v160, v206, s[42:43]
	s_nop 0
	v_cndmask_b32_e32 v159, v159, v161, vcc
	v_cmp_lt_i32_e32 vcc, -1, v156
	s_nop 0
	v_max_u32_dpp v159, v159, v159 row_ror:1 row_mask:0xf bank_mask:0xf bound_ctrl:1
	s_nop 1
	v_max_u32_dpp v159, v159, v159 row_ror:2 row_mask:0xf bank_mask:0xf bound_ctrl:1
	s_nop 1
	v_max_u32_dpp v159, v159, v159 row_ror:4 row_mask:0xf bank_mask:0xf bound_ctrl:1
	s_nop 1
	v_max_u32_dpp v159, v159, v159 row_ror:8 row_mask:0xf bank_mask:0xf bound_ctrl:1
	v_cndmask_b32_e64 v159, v160, v159, s[44:45]
	v_cndmask_b32_e64 v160, v245, -1, vcc
	v_cmp_lt_i32_e32 vcc, -1, v158
	v_bitop3_b32 v160, v160, v156, s83 bitop3:0x78
	v_bitop3_b32 v156, v156, s61, v156 bitop3:0xc
	v_cndmask_b32_e64 v161, v245, -1, vcc
	v_bitop3_b32 v161, v161, v158, s83 bitop3:0x78
	ds_bpermute_b32 v206, v170, v161
	v_bitop3_b32 v158, v158, s61, v158 bitop3:0xc
	s_waitcnt lgkmcnt(0)
; __device__ __forceinline__ void peer_topk(const u32x4 (&scv)[4], const int lane, int (&eidx)[2], float (&gate)[2]) {
;     ...
; #pragma unroll
;     for (int rd = 0; rd < 16; ++rd) {
;       const unsigned wk = rowmax_u(hk);
;       if (li == rd) keep = wk;
;       const bool win = (hk == wk);
;       ptr += win ? 1 : 0;
;       const int pcl = ptr < 15 ? ptr : 15;
;       s2p = __uint_as_float((unsigned)__builtin_amdgcn_ds_bpermute((rbase + pcl) * 4, (int)__float_as_uint(s2)));
;       const unsigned nk = (f_ord(s1 + s2p) & ~0xFFu) | (unsigned)(255 - (li * 16 + pcl));
;       hk = win ? (ptr < 16 ? nk : 0u) : hk;
;     }
	v_add_f32_e32 v206, v160, v206
	v_not_b32_e32 v207, v206
	v_or_b32_e32 v213, 0x80000000, v206
	v_cmp_gt_i32_e32 vcc, 0, v206
	s_nop 1
	v_cndmask_b32_e32 v206, v213, v207, vcc
	v_and_b32_e32 v206, 0xffffff00, v206
	v_bitop3_b32 v206, v206, s89, v171 bitop3:0x36
	s_nop 1
	v_max_u32_dpp v207, v206, v206 row_ror:1 row_mask:0xf bank_mask:0xf bound_ctrl:1
	s_nop 1
	v_max_u32_dpp v207, v207, v207 row_ror:2 row_mask:0xf bank_mask:0xf bound_ctrl:1
	s_nop 1
	v_max_u32_dpp v207, v207, v207 row_ror:4 row_mask:0xf bank_mask:0xf bound_ctrl:1
	s_nop 1
	v_max_u32_dpp v207, v207, v207 row_ror:8 row_mask:0xf bank_mask:0xf bound_ctrl:1
	v_cmp_eq_u32_e32 vcc, v206, v207
	v_cndmask_b32_e64 v213, 0, v207, s[12:13]
	s_nop 0
	v_cndmask_b32_e64 v207, 0, 1, vcc
	v_or_b32_e32 v215, v0, v207
	v_lshlrev_b32_e32 v215, 2, v215
	ds_bpermute_b32 v215, v215, v161
	s_waitcnt lgkmcnt(0)
	v_add_f32_e32 v215, v160, v215
	v_not_b32_e32 v216, v215
	v_or_b32_e32 v217, 0x80000000, v215
	v_cmp_gt_i32_e64 s[0:1], 0, v215
	s_nop 1
	v_cndmask_b32_e64 v215, v217, v216, s[0:1]
	v_and_or_b32 v215, v215, s52, v171
	v_bitop3_b32 v215, v215, s89, v207 bitop3:0x36
	v_cndmask_b32_e32 v206, v206, v215, vcc
	s_nop 1
	v_max_u32_dpp v215, v206, v206 row_ror:1 row_mask:0xf bank_mask:0xf bound_ctrl:1
	s_nop 1
	v_max_u32_dpp v215, v215, v215 row_ror:2 row_mask:0xf bank_mask:0xf bound_ctrl:1
	s_nop 1
	v_max_u32_dpp v215, v215, v215 row_ror:4 row_mask:0xf bank_mask:0xf bound_ctrl:1
	s_nop 1
	v_max_u32_dpp v215, v215, v215 row_ror:8 row_mask:0xf bank_mask:0xf bound_ctrl:1
	v_cmp_eq_u32_e32 vcc, v206, v215
	v_cndmask_b32_e64 v213, v213, v215, s[14:15]
	s_nop 0
	v_addc_co_u32_e64 v217, s[0:1], v0, v207, vcc
	v_lshlrev_b32_e32 v217, 2, v217
	ds_bpermute_b32 v217, v217, v161
	v_addc_co_u32_e64 v216, s[0:1], 0, v207, vcc
	v_cndmask_b32_e64 v215, 0, 1, vcc
	s_waitcnt lgkmcnt(0)
	v_add_f32_e32 v217, v160, v217
	v_not_b32_e32 v218, v217
	v_or_b32_e32 v219, 0x80000000, v217
	v_cmp_gt_i32_e64 s[0:1], 0, v217
	s_nop 1
	v_cndmask_b32_e64 v217, v219, v218, s[0:1]
	v_and_or_b32 v217, v217, s52, v171
	v_addc_co_u32_e64 v217, s[0:1], v217, v207, vcc
	v_xor_b32_e32 v217, 0xff, v217
	v_cndmask_b32_e32 v206, v206, v217, vcc
	s_nop 1
	v_max_u32_dpp v217, v206, v206 row_ror:1 row_mask:0xf bank_mask:0xf bound_ctrl:1
	s_nop 1
	v_max_u32_dpp v217, v217, v217 row_ror:2 row_mask:0xf bank_mask:0xf bound_ctrl:1
	s_nop 1
	v_max_u32_dpp v217, v217, v217 row_ror:4 row_mask:0xf bank_mask:0xf bound_ctrl:1
	s_nop 1
	v_max_u32_dpp v217, v217, v217 row_ror:8 row_mask:0xf bank_mask:0xf bound_ctrl:1
	v_cmp_eq_u32_e32 vcc, v206, v217
	v_cndmask_b32_e64 v213, v213, v217, s[16:17]
	s_nop 0
	v_addc_co_u32_e64 v207, s[0:1], v215, v207, vcc
	v_or_b32_e32 v215, v207, v0
	v_lshlrev_b32_e32 v215, 2, v215
	ds_bpermute_b32 v215, v215, v161
	v_cndmask_b32_e64 v217, 0, 1, vcc
	s_waitcnt lgkmcnt(0)
	v_add_f32_e32 v215, v160, v215
	v_not_b32_e32 v218, v215
	v_or_b32_e32 v219, 0x80000000, v215
	v_cmp_gt_i32_e64 s[0:1], 0, v215
	s_nop 1
	v_cndmask_b32_e64 v215, v219, v218, s[0:1]
	v_and_or_b32 v215, v215, s52, v171
	v_bitop3_b32 v215, v215, s89, v207 bitop3:0x36
	v_cndmask_b32_e32 v206, v206, v215, vcc
	s_nop 1
	v_max_u32_dpp v215, v206, v206 row_ror:1 row_mask:0xf bank_mask:0xf bound_ctrl:1
	s_nop 1
	v_max_u32_dpp v215, v215, v215 row_ror:2 row_mask:0xf bank_mask:0xf bound_ctrl:1
	s_nop 1
	v_max_u32_dpp v215, v215, v215 row_ror:4 row_mask:0xf bank_mask:0xf bound_ctrl:1
	s_nop 1
	v_max_u32_dpp v215, v215, v215 row_ror:8 row_mask:0xf bank_mask:0xf bound_ctrl:1
	v_cmp_eq_u32_e32 vcc, v206, v215
	v_cndmask_b32_e64 v213, v213, v215, s[18:19]
	s_nop 0
	v_addc_co_u32_e64 v216, s[0:1], v216, v217, vcc
	v_or_b32_e32 v217, v216, v0
	v_lshlrev_b32_e32 v217, 2, v217
	ds_bpermute_b32 v217, v217, v161
	v_cndmask_b32_e64 v215, 0, 1, vcc
	s_waitcnt lgkmcnt(0)
	v_add_f32_e32 v217, v160, v217
	v_not_b32_e32 v218, v217
	v_or_b32_e32 v219, 0x80000000, v217
	v_cmp_gt_i32_e64 s[0:1], 0, v217
	s_nop 1
	v_cndmask_b32_e64 v217, v219, v218, s[0:1]
	v_and_or_b32 v217, v217, s52, v171
	v_bitop3_b32 v217, v217, s89, v216 bitop3:0x36
	v_cndmask_b32_e32 v206, v206, v217, vcc
	s_nop 1
	v_max_u32_dpp v217, v206, v206 row_ror:1 row_mask:0xf bank_mask:0xf bound_ctrl:1
	s_nop 1
	v_max_u32_dpp v217, v217, v217 row_ror:2 row_mask:0xf bank_mask:0xf bound_ctrl:1
	s_nop 1
	v_max_u32_dpp v217, v217, v217 row_ror:4 row_mask:0xf bank_mask:0xf bound_ctrl:1
	s_nop 1
	v_max_u32_dpp v217, v217, v217 row_ror:8 row_mask:0xf bank_mask:0xf bound_ctrl:1
	v_cmp_eq_u32_e32 vcc, v206, v217
	v_cndmask_b32_e64 v213, v213, v217, s[20:21]
	s_nop 0
	v_addc_co_u32_e64 v207, s[0:1], v207, v215, vcc
	v_add_lshl_u32 v215, v207, v0, 2
	ds_bpermute_b32 v215, v215, v161
	v_cndmask_b32_e64 v217, 0, 1, vcc
	s_waitcnt lgkmcnt(0)
	v_add_f32_e32 v215, v160, v215
	v_not_b32_e32 v218, v215
	v_or_b32_e32 v219, 0x80000000, v215
	v_cmp_gt_i32_e64 s[0:1], 0, v215
	s_nop 1
	v_cndmask_b32_e64 v215, v219, v218, s[0:1]
	v_and_or_b32 v215, v215, s52, v171
	v_bitop3_b32 v215, v215, s89, v207 bitop3:0x36
	v_cndmask_b32_e32 v206, v206, v215, vcc
	s_nop 1
	v_max_u32_dpp v215, v206, v206 row_ror:1 row_mask:0xf bank_mask:0xf bound_ctrl:1
	s_nop 1
	v_max_u32_dpp v215, v215, v215 row_ror:2 row_mask:0xf bank_mask:0xf bound_ctrl:1
	s_nop 1
	v_max_u32_dpp v215, v215, v215 row_ror:4 row_mask:0xf bank_mask:0xf bound_ctrl:1
	s_nop 1
	v_max_u32_dpp v215, v215, v215 row_ror:8 row_mask:0xf bank_mask:0xf bound_ctrl:1
	v_cmp_eq_u32_e32 vcc, v206, v215
	v_cndmask_b32_e64 v213, v213, v215, s[22:23]
	s_nop 0
	v_addc_co_u32_e64 v216, s[0:1], v216, v217, vcc
	v_add_lshl_u32 v217, v216, v0, 2
	ds_bpermute_b32 v217, v217, v161
	v_cndmask_b32_e64 v215, 0, 1, vcc
	s_waitcnt lgkmcnt(0)
; __device__ __forceinline__ void peer_topk(const u32x4 (&scv)[4], const int lane, int (&eidx)[2], float (&gate)[2]) {
;     ...
; #pragma unroll
;     for (int rd = 0; rd < 16; ++rd) {
;       const unsigned wk = rowmax_u(hk);
;       if (li == rd) keep = wk;
;       const bool win = (hk == wk);
;       ptr += win ? 1 : 0;
;       const int pcl = ptr < 15 ? ptr : 15;
;       s2p = __uint_as_float((unsigned)__builtin_amdgcn_ds_bpermute((rbase + pcl) * 4, (int)__float_as_uint(s2)));
;       const unsigned nk = (f_ord(s1 + s2p) & ~0xFFu) | (unsigned)(255 - (li * 16 + pcl));
;       hk = win ? (ptr < 16 ? nk : 0u) : hk;
;     }
	v_add_f32_e32 v217, v160, v217
	v_not_b32_e32 v218, v217
	v_or_b32_e32 v219, 0x80000000, v217
	v_cmp_gt_i32_e64 s[0:1], 0, v217
	s_nop 1
	v_cndmask_b32_e64 v217, v219, v218, s[0:1]
	v_and_or_b32 v217, v217, s52, v171
	v_bitop3_b32 v217, v217, s89, v216 bitop3:0x36
	v_cndmask_b32_e32 v206, v206, v217, vcc
	s_nop 1
	v_max_u32_dpp v217, v206, v206 row_ror:1 row_mask:0xf bank_mask:0xf bound_ctrl:1
	s_nop 1
	v_max_u32_dpp v217, v217, v217 row_ror:2 row_mask:0xf bank_mask:0xf bound_ctrl:1
	s_nop 1
	v_max_u32_dpp v217, v217, v217 row_ror:4 row_mask:0xf bank_mask:0xf bound_ctrl:1
	s_nop 1
	v_max_u32_dpp v217, v217, v217 row_ror:8 row_mask:0xf bank_mask:0xf bound_ctrl:1
	v_cmp_eq_u32_e32 vcc, v206, v217
	v_cndmask_b32_e64 v213, v213, v217, s[24:25]
	s_nop 0
	v_addc_co_u32_e64 v207, s[0:1], v207, v215, vcc
	v_add_lshl_u32 v215, v207, v0, 2
	ds_bpermute_b32 v215, v215, v161
	v_cndmask_b32_e64 v217, 0, 1, vcc
	s_waitcnt lgkmcnt(0)
	v_add_f32_e32 v215, v160, v215
	v_not_b32_e32 v218, v215
	v_or_b32_e32 v219, 0x80000000, v215
	v_cmp_gt_i32_e64 s[0:1], 0, v215
	s_nop 1
	v_cndmask_b32_e64 v215, v219, v218, s[0:1]
	v_and_or_b32 v215, v215, s52, v171
	v_bitop3_b32 v215, v215, s89, v207 bitop3:0x36
	v_cndmask_b32_e32 v206, v206, v215, vcc
	s_nop 1
	v_max_u32_dpp v215, v206, v206 row_ror:1 row_mask:0xf bank_mask:0xf bound_ctrl:1
	s_nop 1
	v_max_u32_dpp v215, v215, v215 row_ror:2 row_mask:0xf bank_mask:0xf bound_ctrl:1
	s_nop 1
	v_max_u32_dpp v215, v215, v215 row_ror:4 row_mask:0xf bank_mask:0xf bound_ctrl:1
	s_nop 1
	v_max_u32_dpp v215, v215, v215 row_ror:8 row_mask:0xf bank_mask:0xf bound_ctrl:1
	v_cmp_eq_u32_e32 vcc, v206, v215
	v_cndmask_b32_e64 v213, v213, v215, s[26:27]
	s_nop 0
	v_addc_co_u32_e64 v216, s[0:1], v216, v217, vcc
	v_add_lshl_u32 v217, v216, v0, 2
	ds_bpermute_b32 v217, v217, v161
	v_cndmask_b32_e64 v215, 0, 1, vcc
	s_waitcnt lgkmcnt(0)
	v_add_f32_e32 v217, v160, v217
	v_not_b32_e32 v218, v217
	v_or_b32_e32 v219, 0x80000000, v217
	v_cmp_gt_i32_e64 s[0:1], 0, v217
	s_nop 1
	v_cndmask_b32_e64 v217, v219, v218, s[0:1]
	v_and_or_b32 v217, v217, s52, v171
	v_bitop3_b32 v217, v217, s89, v216 bitop3:0x36
	v_cndmask_b32_e32 v206, v206, v217, vcc
	s_nop 1
	v_max_u32_dpp v217, v206, v206 row_ror:1 row_mask:0xf bank_mask:0xf bound_ctrl:1
	s_nop 1
	v_max_u32_dpp v217, v217, v217 row_ror:2 row_mask:0xf bank_mask:0xf bound_ctrl:1
	s_nop 1
	v_max_u32_dpp v217, v217, v217 row_ror:4 row_mask:0xf bank_mask:0xf bound_ctrl:1
	s_nop 1
	v_max_u32_dpp v217, v217, v217 row_ror:8 row_mask:0xf bank_mask:0xf bound_ctrl:1
	v_cmp_eq_u32_e32 vcc, v206, v217
	v_cndmask_b32_e64 v213, v213, v217, s[28:29]
	s_nop 0
	v_addc_co_u32_e64 v207, s[0:1], v207, v215, vcc
	v_add_lshl_u32 v215, v207, v0, 2
	ds_bpermute_b32 v215, v215, v161
	v_cndmask_b32_e64 v217, 0, 1, vcc
	s_waitcnt lgkmcnt(0)
	v_add_f32_e32 v215, v160, v215
	v_not_b32_e32 v218, v215
	v_or_b32_e32 v219, 0x80000000, v215
	v_cmp_gt_i32_e64 s[0:1], 0, v215
	s_nop 1
	v_cndmask_b32_e64 v215, v219, v218, s[0:1]
	v_and_or_b32 v215, v215, s52, v171
	v_bitop3_b32 v215, v215, s89, v207 bitop3:0x36
	v_cndmask_b32_e32 v206, v206, v215, vcc
	s_nop 1
	v_max_u32_dpp v215, v206, v206 row_ror:1 row_mask:0xf bank_mask:0xf bound_ctrl:1
	s_nop 1
	v_max_u32_dpp v215, v215, v215 row_ror:2 row_mask:0xf bank_mask:0xf bound_ctrl:1
	s_nop 1
	v_max_u32_dpp v215, v215, v215 row_ror:4 row_mask:0xf bank_mask:0xf bound_ctrl:1
	s_nop 1
	v_max_u32_dpp v215, v215, v215 row_ror:8 row_mask:0xf bank_mask:0xf bound_ctrl:1
	v_cmp_eq_u32_e32 vcc, v206, v215
	v_cndmask_b32_e64 v213, v213, v215, s[30:31]
	s_nop 0
	v_addc_co_u32_e64 v216, s[0:1], v216, v217, vcc
	v_add_lshl_u32 v217, v216, v0, 2
	ds_bpermute_b32 v217, v217, v161
	v_cndmask_b32_e64 v215, 0, 1, vcc
	s_waitcnt lgkmcnt(0)
	v_add_f32_e32 v217, v160, v217
	v_not_b32_e32 v218, v217
	v_or_b32_e32 v219, 0x80000000, v217
	v_cmp_gt_i32_e64 s[0:1], 0, v217
	s_nop 1
	v_cndmask_b32_e64 v217, v219, v218, s[0:1]
	v_and_or_b32 v217, v217, s52, v171
	v_bitop3_b32 v217, v217, s89, v216 bitop3:0x36
	v_cndmask_b32_e32 v206, v206, v217, vcc
	s_nop 1
	v_max_u32_dpp v217, v206, v206 row_ror:1 row_mask:0xf bank_mask:0xf bound_ctrl:1
	s_nop 1
	v_max_u32_dpp v217, v217, v217 row_ror:2 row_mask:0xf bank_mask:0xf bound_ctrl:1
	s_nop 1
	v_max_u32_dpp v217, v217, v217 row_ror:4 row_mask:0xf bank_mask:0xf bound_ctrl:1
	s_nop 1
	v_max_u32_dpp v217, v217, v217 row_ror:8 row_mask:0xf bank_mask:0xf bound_ctrl:1
	v_cmp_eq_u32_e32 vcc, v206, v217
	v_cndmask_b32_e64 v213, v213, v217, s[34:35]
	s_nop 0
	v_addc_co_u32_e64 v207, s[0:1], v207, v215, vcc
	v_add_lshl_u32 v215, v207, v0, 2
	ds_bpermute_b32 v215, v215, v161
	v_cndmask_b32_e64 v217, 0, 1, vcc
	s_waitcnt lgkmcnt(0)
	v_add_f32_e32 v215, v160, v215
	v_not_b32_e32 v218, v215
	v_or_b32_e32 v219, 0x80000000, v215
	v_cmp_gt_i32_e64 s[0:1], 0, v215
	s_nop 1
	v_cndmask_b32_e64 v215, v219, v218, s[0:1]
	v_and_or_b32 v215, v215, s52, v171
	v_bitop3_b32 v215, v215, s89, v207 bitop3:0x36
	v_cndmask_b32_e32 v206, v206, v215, vcc
	s_nop 1
	v_max_u32_dpp v215, v206, v206 row_ror:1 row_mask:0xf bank_mask:0xf bound_ctrl:1
	s_nop 1
	v_max_u32_dpp v215, v215, v215 row_ror:2 row_mask:0xf bank_mask:0xf bound_ctrl:1
	s_nop 1
	v_max_u32_dpp v215, v215, v215 row_ror:4 row_mask:0xf bank_mask:0xf bound_ctrl:1
	s_nop 1
	v_max_u32_dpp v215, v215, v215 row_ror:8 row_mask:0xf bank_mask:0xf bound_ctrl:1
	v_cmp_eq_u32_e32 vcc, v206, v215
	v_cndmask_b32_e64 v213, v213, v215, s[36:37]
	s_nop 0
	v_addc_co_u32_e64 v216, s[0:1], v216, v217, vcc
	v_add_lshl_u32 v217, v216, v0, 2
	ds_bpermute_b32 v217, v217, v161
	v_cndmask_b32_e64 v215, 0, 1, vcc
	s_waitcnt lgkmcnt(0)
; __device__ __forceinline__ void peer_topk(const u32x4 (&scv)[4], const int lane, int (&eidx)[2], float (&gate)[2]) {
;     ...
; #pragma unroll
;     for (int rd = 0; rd < 16; ++rd) {
;       const unsigned wk = rowmax_u(hk);
;       if (li == rd) keep = wk;
;       const bool win = (hk == wk);
;       ptr += win ? 1 : 0;
;       const int pcl = ptr < 15 ? ptr : 15;
;       s2p = __uint_as_float((unsigned)__builtin_amdgcn_ds_bpermute((rbase + pcl) * 4, (int)__float_as_uint(s2)));
;       const unsigned nk = (f_ord(s1 + s2p) & ~0xFFu) | (unsigned)(255 - (li * 16 + pcl));
;       hk = win ? (ptr < 16 ? nk : 0u) : hk;
;     }
;     const float ts = f_deord(keep & ~0xFFu);
;     const int idx8 = 255 - (int)(keep & 0xFFu);
;     const int a = idx8 >> 4, bq = idx8 & 15;
;     const int e1 = __builtin_amdgcn_ds_bpermute((rbase + a) * 4, i1);
;     const int e2 = __builtin_amdgcn_ds_bpermute((rbase + bq) * 4, i2);
;     eidx[hp2] = e1 * 128 + e2;
;     const float tmax = f_deord(rowmax_u(keep) & ~0xFFu);
;     const float ex = __expf(ts - tmax);
;     const float sm = rowsum_f(ex);
;     gate[hp2] = ex / sm;
	v_add_f32_e32 v217, v160, v217
	v_not_b32_e32 v218, v217
	v_or_b32_e32 v219, 0x80000000, v217
	v_cmp_gt_i32_e64 s[0:1], 0, v217
	s_nop 1
	v_cndmask_b32_e64 v217, v219, v218, s[0:1]
	v_and_or_b32 v217, v217, s52, v171
	v_bitop3_b32 v217, v217, s89, v216 bitop3:0x36
	v_cndmask_b32_e32 v206, v206, v217, vcc
	s_nop 1
	v_max_u32_dpp v217, v206, v206 row_ror:1 row_mask:0xf bank_mask:0xf bound_ctrl:1
	s_nop 1
	v_max_u32_dpp v217, v217, v217 row_ror:2 row_mask:0xf bank_mask:0xf bound_ctrl:1
	s_nop 1
	v_max_u32_dpp v217, v217, v217 row_ror:4 row_mask:0xf bank_mask:0xf bound_ctrl:1
	s_nop 1
	v_max_u32_dpp v217, v217, v217 row_ror:8 row_mask:0xf bank_mask:0xf bound_ctrl:1
	v_cmp_eq_u32_e32 vcc, v206, v217
	v_cndmask_b32_e64 v213, v213, v217, s[38:39]
	s_nop 0
	v_addc_co_u32_e64 v207, s[0:1], v207, v215, vcc
	v_add_lshl_u32 v215, v207, v0, 2
	ds_bpermute_b32 v215, v215, v161
	v_cndmask_b32_e64 v217, 0, 1, vcc
	s_waitcnt lgkmcnt(0)
	v_add_f32_e32 v215, v160, v215
	v_not_b32_e32 v218, v215
	v_or_b32_e32 v219, 0x80000000, v215
	v_cmp_gt_i32_e64 s[0:1], 0, v215
	s_nop 1
	v_cndmask_b32_e64 v215, v219, v218, s[0:1]
	v_and_or_b32 v215, v215, s52, v171
	v_bitop3_b32 v215, v215, s89, v207 bitop3:0x36
	v_cndmask_b32_e32 v206, v206, v215, vcc
	s_nop 1
	v_max_u32_dpp v215, v206, v206 row_ror:1 row_mask:0xf bank_mask:0xf bound_ctrl:1
	s_nop 1
	v_max_u32_dpp v215, v215, v215 row_ror:2 row_mask:0xf bank_mask:0xf bound_ctrl:1
	s_nop 1
	v_max_u32_dpp v215, v215, v215 row_ror:4 row_mask:0xf bank_mask:0xf bound_ctrl:1
	s_nop 1
	v_max_u32_dpp v215, v215, v215 row_ror:8 row_mask:0xf bank_mask:0xf bound_ctrl:1
	v_cmp_eq_u32_e32 vcc, v206, v215
	v_cndmask_b32_e64 v213, v213, v215, s[40:41]
	s_nop 0
	v_addc_co_u32_e64 v216, s[0:1], v216, v217, vcc
	v_add_lshl_u32 v217, v216, v0, 2
	ds_bpermute_b32 v217, v217, v161
	v_cndmask_b32_e64 v215, 0, 1, vcc
	s_waitcnt lgkmcnt(0)
	v_add_f32_e32 v217, v160, v217
	v_not_b32_e32 v218, v217
	v_or_b32_e32 v219, 0x80000000, v217
	v_cmp_gt_i32_e64 s[0:1], 0, v217
	s_nop 1
	v_cndmask_b32_e64 v217, v219, v218, s[0:1]
	v_and_or_b32 v217, v217, s52, v171
	v_bitop3_b32 v216, v217, s89, v216 bitop3:0x36
	v_cndmask_b32_e32 v206, v206, v216, vcc
	s_nop 1
	v_max_u32_dpp v216, v206, v206 row_ror:1 row_mask:0xf bank_mask:0xf bound_ctrl:1
	s_nop 1
	v_max_u32_dpp v216, v216, v216 row_ror:2 row_mask:0xf bank_mask:0xf bound_ctrl:1
	s_nop 1
	v_max_u32_dpp v216, v216, v216 row_ror:4 row_mask:0xf bank_mask:0xf bound_ctrl:1
	s_nop 1
	v_max_u32_dpp v216, v216, v216 row_ror:8 row_mask:0xf bank_mask:0xf bound_ctrl:1
	v_cmp_eq_u32_e32 vcc, v206, v216
	v_cndmask_b32_e64 v213, v213, v216, s[42:43]
	s_nop 0
	v_addc_co_u32_e64 v207, s[0:1], v207, v215, vcc
	v_add_lshl_u32 v215, v207, v0, 2
	ds_bpermute_b32 v161, v215, v161
	s_waitcnt lgkmcnt(0)
	v_add_f32_e32 v160, v160, v161
	v_not_b32_e32 v161, v160
	v_or_b32_e32 v215, 0x80000000, v160
	v_cmp_gt_i32_e64 s[0:1], 0, v160
	s_nop 1
	v_cndmask_b32_e64 v160, v215, v161, s[0:1]
	v_and_or_b32 v160, v160, s52, v171
	v_bitop3_b32 v160, v160, s89, v207 bitop3:0x36
	v_cndmask_b32_e32 v160, v206, v160, vcc
	s_nop 1
	v_max_u32_dpp v160, v160, v160 row_ror:1 row_mask:0xf bank_mask:0xf bound_ctrl:1
	s_nop 1
	v_max_u32_dpp v160, v160, v160 row_ror:2 row_mask:0xf bank_mask:0xf bound_ctrl:1
	s_nop 1
	v_max_u32_dpp v160, v160, v160 row_ror:4 row_mask:0xf bank_mask:0xf bound_ctrl:1
	s_nop 1
	v_max_u32_dpp v160, v160, v160 row_ror:8 row_mask:0xf bank_mask:0xf bound_ctrl:1
	v_cndmask_b32_e64 v160, v213, v160, s[44:45]
	v_not_b32_e32 v161, v160
	v_lshrrev_b32_e32 v161, 4, v161
	v_and_or_b32 v161, v161, 15, v0
	v_lshlrev_b32_e32 v161, 2, v161
	ds_bpermute_b32 v156, v161, v156
	v_bitop3_b32 v161, v160, v0, 15 bitop3:0xce
	v_lshlrev_b32_e32 v161, 2, v161
	ds_bpermute_b32 v158, v161, v158
	v_cmp_lt_i32_e64 s[0:1], -1, v160
	v_and_b32_e32 v206, 0xffffff00, v160
	s_waitcnt lgkmcnt(0)
	v_lshl_add_u32 v156, v156, 7, v158
	v_max_u32_dpp v158, v160, v160 row_ror:1 row_mask:0xf bank_mask:0xf bound_ctrl:1
	v_cndmask_b32_e64 v160, v245, -1, s[0:1]
	v_xor_b32_e32 v160, v160, v206
	v_max_u32_dpp v158, v158, v158 row_ror:2 row_mask:0xf bank_mask:0xf bound_ctrl:1
	s_nop 1
	v_max_u32_dpp v158, v158, v158 row_ror:4 row_mask:0xf bank_mask:0xf bound_ctrl:1
	s_nop 1
	v_max_u32_dpp v158, v158, v158 row_ror:8 row_mask:0xf bank_mask:0xf bound_ctrl:1
	v_cmp_lt_i32_e32 vcc, -1, v158
	v_and_b32_e32 v161, 0xffffff00, v158
	s_nop 0
	v_cndmask_b32_e64 v158, v245, -1, vcc
	v_cmp_lt_i32_e32 vcc, -1, v157
	v_xor_b32_e32 v158, v158, v161
	v_sub_f32_e32 v158, v160, v158
	v_cndmask_b32_e64 v161, v245, -1, vcc
	v_cmp_lt_i32_e32 vcc, -1, v159
	v_bitop3_b32 v161, v161, v157, s83 bitop3:0x78
	v_bitop3_b32 v157, v157, s61, v157 bitop3:0xc
	v_cndmask_b32_e64 v206, v245, -1, vcc
	v_bitop3_b32 v206, v206, v159, s83 bitop3:0x78
	ds_bpermute_b32 v207, v170, v206
	v_bitop3_b32 v159, v159, s61, v159 bitop3:0xc
	v_mul_f32_e32 v158, 0x3fb8aa3b, v158
	v_exp_f32_e32 v158, v158
	v_mov_b32_e32 v160, 0
	s_waitcnt lgkmcnt(0)
	v_add_f32_e32 v207, v161, v207
	v_not_b32_e32 v213, v207
	v_or_b32_e32 v215, 0x80000000, v207
	v_cmp_gt_i32_e32 vcc, 0, v207
	v_mov_b32_dpp v160, v158 row_ror:1 row_mask:0xf bank_mask:0xf
	s_nop 0
	v_cndmask_b32_e32 v207, v215, v213, vcc
	v_and_b32_e32 v207, 0xffffff00, v207
	v_bitop3_b32 v207, v207, s89, v171 bitop3:0x36
	s_nop 1
	v_max_u32_dpp v213, v207, v207 row_ror:1 row_mask:0xf bank_mask:0xf bound_ctrl:1
	s_nop 1
	v_max_u32_dpp v213, v213, v213 row_ror:2 row_mask:0xf bank_mask:0xf bound_ctrl:1
	s_nop 1
	v_max_u32_dpp v213, v213, v213 row_ror:4 row_mask:0xf bank_mask:0xf bound_ctrl:1
	s_nop 1
	v_max_u32_dpp v213, v213, v213 row_ror:8 row_mask:0xf bank_mask:0xf bound_ctrl:1
	v_cmp_eq_u32_e32 vcc, v207, v213
	v_cndmask_b32_e64 v215, 0, v213, s[12:13]
	s_nop 0
	v_cndmask_b32_e64 v213, 0, 1, vcc
	v_or_b32_e32 v216, v0, v213
	v_lshlrev_b32_e32 v216, 2, v216
	ds_bpermute_b32 v216, v216, v206
	s_waitcnt lgkmcnt(0)
; __device__ __forceinline__ void peer_topk(const u32x4 (&scv)[4], const int lane, int (&eidx)[2], float (&gate)[2]) {
;     ...
; #pragma unroll
;     for (int rd = 0; rd < 16; ++rd) {
;       const unsigned wk = rowmax_u(hk);
;       if (li == rd) keep = wk;
;       const bool win = (hk == wk);
;       ptr += win ? 1 : 0;
;       const int pcl = ptr < 15 ? ptr : 15;
;       s2p = __uint_as_float((unsigned)__builtin_amdgcn_ds_bpermute((rbase + pcl) * 4, (int)__float_as_uint(s2)));
;       const unsigned nk = (f_ord(s1 + s2p) & ~0xFFu) | (unsigned)(255 - (li * 16 + pcl));
;       hk = win ? (ptr < 16 ? nk : 0u) : hk;
;     }
	v_add_f32_e32 v216, v161, v216
	v_not_b32_e32 v217, v216
	v_or_b32_e32 v218, 0x80000000, v216
	v_cmp_gt_i32_e64 s[0:1], 0, v216
	s_nop 1
	v_cndmask_b32_e64 v216, v218, v217, s[0:1]
	v_and_or_b32 v216, v216, s52, v171
	v_bitop3_b32 v216, v216, s89, v213 bitop3:0x36
	v_cndmask_b32_e32 v207, v207, v216, vcc
	s_nop 1
	v_max_u32_dpp v216, v207, v207 row_ror:1 row_mask:0xf bank_mask:0xf bound_ctrl:1
	s_nop 1
	v_max_u32_dpp v216, v216, v216 row_ror:2 row_mask:0xf bank_mask:0xf bound_ctrl:1
	s_nop 1
	v_max_u32_dpp v216, v216, v216 row_ror:4 row_mask:0xf bank_mask:0xf bound_ctrl:1
	s_nop 1
	v_max_u32_dpp v216, v216, v216 row_ror:8 row_mask:0xf bank_mask:0xf bound_ctrl:1
	v_cmp_eq_u32_e32 vcc, v207, v216
	v_cndmask_b32_e64 v215, v215, v216, s[14:15]
	s_nop 0
	v_addc_co_u32_e64 v218, s[0:1], v0, v213, vcc
	v_lshlrev_b32_e32 v218, 2, v218
	ds_bpermute_b32 v218, v218, v206
	v_addc_co_u32_e64 v217, s[0:1], 0, v213, vcc
	v_cndmask_b32_e64 v216, 0, 1, vcc
	s_waitcnt lgkmcnt(0)
	v_add_f32_e32 v218, v161, v218
	v_not_b32_e32 v219, v218
	v_or_b32_e32 v220, 0x80000000, v218
	v_cmp_gt_i32_e64 s[0:1], 0, v218
	s_nop 1
	v_cndmask_b32_e64 v218, v220, v219, s[0:1]
	v_and_or_b32 v218, v218, s52, v171
	v_addc_co_u32_e64 v218, s[0:1], v218, v213, vcc
	v_xor_b32_e32 v218, 0xff, v218
	v_cndmask_b32_e32 v207, v207, v218, vcc
	s_nop 1
	v_max_u32_dpp v218, v207, v207 row_ror:1 row_mask:0xf bank_mask:0xf bound_ctrl:1
	s_nop 1
	v_max_u32_dpp v218, v218, v218 row_ror:2 row_mask:0xf bank_mask:0xf bound_ctrl:1
	s_nop 1
	v_max_u32_dpp v218, v218, v218 row_ror:4 row_mask:0xf bank_mask:0xf bound_ctrl:1
	s_nop 1
	v_max_u32_dpp v218, v218, v218 row_ror:8 row_mask:0xf bank_mask:0xf bound_ctrl:1
	v_cmp_eq_u32_e32 vcc, v207, v218
	v_cndmask_b32_e64 v215, v215, v218, s[16:17]
	s_nop 0
	v_addc_co_u32_e64 v213, s[0:1], v216, v213, vcc
	v_or_b32_e32 v216, v213, v0
	v_lshlrev_b32_e32 v216, 2, v216
	ds_bpermute_b32 v216, v216, v206
	v_cndmask_b32_e64 v218, 0, 1, vcc
	s_waitcnt lgkmcnt(0)
	v_add_f32_e32 v216, v161, v216
	v_not_b32_e32 v219, v216
	v_or_b32_e32 v220, 0x80000000, v216
	v_cmp_gt_i32_e64 s[0:1], 0, v216
	s_nop 1
	v_cndmask_b32_e64 v216, v220, v219, s[0:1]
	v_and_or_b32 v216, v216, s52, v171
	v_bitop3_b32 v216, v216, s89, v213 bitop3:0x36
	v_cndmask_b32_e32 v207, v207, v216, vcc
	s_nop 1
	v_max_u32_dpp v216, v207, v207 row_ror:1 row_mask:0xf bank_mask:0xf bound_ctrl:1
	s_nop 1
	v_max_u32_dpp v216, v216, v216 row_ror:2 row_mask:0xf bank_mask:0xf bound_ctrl:1
	s_nop 1
	v_max_u32_dpp v216, v216, v216 row_ror:4 row_mask:0xf bank_mask:0xf bound_ctrl:1
	s_nop 1
	v_max_u32_dpp v216, v216, v216 row_ror:8 row_mask:0xf bank_mask:0xf bound_ctrl:1
	v_cmp_eq_u32_e32 vcc, v207, v216
	v_cndmask_b32_e64 v215, v215, v216, s[18:19]
	s_nop 0
	v_addc_co_u32_e64 v217, s[0:1], v217, v218, vcc
	v_or_b32_e32 v218, v217, v0
	v_lshlrev_b32_e32 v218, 2, v218
	ds_bpermute_b32 v218, v218, v206
	v_cndmask_b32_e64 v216, 0, 1, vcc
	s_waitcnt lgkmcnt(0)
	v_add_f32_e32 v218, v161, v218
	v_not_b32_e32 v219, v218
	v_or_b32_e32 v220, 0x80000000, v218
	v_cmp_gt_i32_e64 s[0:1], 0, v218
	s_nop 1
	v_cndmask_b32_e64 v218, v220, v219, s[0:1]
	v_and_or_b32 v218, v218, s52, v171
	v_bitop3_b32 v218, v218, s89, v217 bitop3:0x36
	v_cndmask_b32_e32 v207, v207, v218, vcc
	s_nop 1
	v_max_u32_dpp v218, v207, v207 row_ror:1 row_mask:0xf bank_mask:0xf bound_ctrl:1
	s_nop 1
	v_max_u32_dpp v218, v218, v218 row_ror:2 row_mask:0xf bank_mask:0xf bound_ctrl:1
	s_nop 1
	v_max_u32_dpp v218, v218, v218 row_ror:4 row_mask:0xf bank_mask:0xf bound_ctrl:1
	s_nop 1
	v_max_u32_dpp v218, v218, v218 row_ror:8 row_mask:0xf bank_mask:0xf bound_ctrl:1
	v_cmp_eq_u32_e32 vcc, v207, v218
	v_cndmask_b32_e64 v215, v215, v218, s[20:21]
	s_nop 0
	v_addc_co_u32_e64 v213, s[0:1], v213, v216, vcc
	v_add_lshl_u32 v216, v213, v0, 2
	ds_bpermute_b32 v216, v216, v206
	v_cndmask_b32_e64 v218, 0, 1, vcc
	s_waitcnt lgkmcnt(0)
	v_add_f32_e32 v216, v161, v216
	v_not_b32_e32 v219, v216
	v_or_b32_e32 v220, 0x80000000, v216
	v_cmp_gt_i32_e64 s[0:1], 0, v216
	s_nop 1
	v_cndmask_b32_e64 v216, v220, v219, s[0:1]
	v_and_or_b32 v216, v216, s52, v171
	v_bitop3_b32 v216, v216, s89, v213 bitop3:0x36
	v_cndmask_b32_e32 v207, v207, v216, vcc
	s_nop 1
	v_max_u32_dpp v216, v207, v207 row_ror:1 row_mask:0xf bank_mask:0xf bound_ctrl:1
	s_nop 1
	v_max_u32_dpp v216, v216, v216 row_ror:2 row_mask:0xf bank_mask:0xf bound_ctrl:1
	s_nop 1
	v_max_u32_dpp v216, v216, v216 row_ror:4 row_mask:0xf bank_mask:0xf bound_ctrl:1
	s_nop 1
	v_max_u32_dpp v216, v216, v216 row_ror:8 row_mask:0xf bank_mask:0xf bound_ctrl:1
	v_cmp_eq_u32_e32 vcc, v207, v216
	v_cndmask_b32_e64 v215, v215, v216, s[22:23]
	s_nop 0
	v_addc_co_u32_e64 v217, s[0:1], v217, v218, vcc
	v_add_lshl_u32 v218, v217, v0, 2
	ds_bpermute_b32 v218, v218, v206
	v_cndmask_b32_e64 v216, 0, 1, vcc
	s_waitcnt lgkmcnt(0)
	v_add_f32_e32 v218, v161, v218
	v_not_b32_e32 v219, v218
	v_or_b32_e32 v220, 0x80000000, v218
	v_cmp_gt_i32_e64 s[0:1], 0, v218
	s_nop 1
	v_cndmask_b32_e64 v218, v220, v219, s[0:1]
	v_and_or_b32 v218, v218, s52, v171
	v_bitop3_b32 v218, v218, s89, v217 bitop3:0x36
	v_cndmask_b32_e32 v207, v207, v218, vcc
	s_nop 1
	v_max_u32_dpp v218, v207, v207 row_ror:1 row_mask:0xf bank_mask:0xf bound_ctrl:1
	s_nop 1
	v_max_u32_dpp v218, v218, v218 row_ror:2 row_mask:0xf bank_mask:0xf bound_ctrl:1
	s_nop 1
	v_max_u32_dpp v218, v218, v218 row_ror:4 row_mask:0xf bank_mask:0xf bound_ctrl:1
	s_nop 1
	v_max_u32_dpp v218, v218, v218 row_ror:8 row_mask:0xf bank_mask:0xf bound_ctrl:1
	v_cmp_eq_u32_e32 vcc, v207, v218
	v_cndmask_b32_e64 v215, v215, v218, s[24:25]
	s_nop 0
	v_addc_co_u32_e64 v213, s[0:1], v213, v216, vcc
	v_add_lshl_u32 v216, v213, v0, 2
	ds_bpermute_b32 v216, v216, v206
	v_cndmask_b32_e64 v218, 0, 1, vcc
	s_waitcnt lgkmcnt(0)
; __device__ __forceinline__ void peer_topk(const u32x4 (&scv)[4], const int lane, int (&eidx)[2], float (&gate)[2]) {
;     ...
; #pragma unroll
;     for (int rd = 0; rd < 16; ++rd) {
;       const unsigned wk = rowmax_u(hk);
;       if (li == rd) keep = wk;
;       const bool win = (hk == wk);
;       ptr += win ? 1 : 0;
;       const int pcl = ptr < 15 ? ptr : 15;
;       s2p = __uint_as_float((unsigned)__builtin_amdgcn_ds_bpermute((rbase + pcl) * 4, (int)__float_as_uint(s2)));
;       const unsigned nk = (f_ord(s1 + s2p) & ~0xFFu) | (unsigned)(255 - (li * 16 + pcl));
;       hk = win ? (ptr < 16 ? nk : 0u) : hk;
;     }
	v_add_f32_e32 v216, v161, v216
	v_not_b32_e32 v219, v216
	v_or_b32_e32 v220, 0x80000000, v216
	v_cmp_gt_i32_e64 s[0:1], 0, v216
	s_nop 1
	v_cndmask_b32_e64 v216, v220, v219, s[0:1]
	v_and_or_b32 v216, v216, s52, v171
	v_bitop3_b32 v216, v216, s89, v213 bitop3:0x36
	v_cndmask_b32_e32 v207, v207, v216, vcc
	s_nop 1
	v_max_u32_dpp v216, v207, v207 row_ror:1 row_mask:0xf bank_mask:0xf bound_ctrl:1
	s_nop 1
	v_max_u32_dpp v216, v216, v216 row_ror:2 row_mask:0xf bank_mask:0xf bound_ctrl:1
	s_nop 1
	v_max_u32_dpp v216, v216, v216 row_ror:4 row_mask:0xf bank_mask:0xf bound_ctrl:1
	s_nop 1
	v_max_u32_dpp v216, v216, v216 row_ror:8 row_mask:0xf bank_mask:0xf bound_ctrl:1
	v_cmp_eq_u32_e32 vcc, v207, v216
	v_cndmask_b32_e64 v215, v215, v216, s[26:27]
	s_nop 0
	v_addc_co_u32_e64 v217, s[0:1], v217, v218, vcc
	v_add_lshl_u32 v218, v217, v0, 2
	ds_bpermute_b32 v218, v218, v206
	v_cndmask_b32_e64 v216, 0, 1, vcc
	s_waitcnt lgkmcnt(0)
	v_add_f32_e32 v218, v161, v218
	v_not_b32_e32 v219, v218
	v_or_b32_e32 v220, 0x80000000, v218
	v_cmp_gt_i32_e64 s[0:1], 0, v218
	s_nop 1
	v_cndmask_b32_e64 v218, v220, v219, s[0:1]
	v_and_or_b32 v218, v218, s52, v171
	v_bitop3_b32 v218, v218, s89, v217 bitop3:0x36
	v_cndmask_b32_e32 v207, v207, v218, vcc
	s_nop 1
	v_max_u32_dpp v218, v207, v207 row_ror:1 row_mask:0xf bank_mask:0xf bound_ctrl:1
	s_nop 1
	v_max_u32_dpp v218, v218, v218 row_ror:2 row_mask:0xf bank_mask:0xf bound_ctrl:1
	s_nop 1
	v_max_u32_dpp v218, v218, v218 row_ror:4 row_mask:0xf bank_mask:0xf bound_ctrl:1
	s_nop 1
	v_max_u32_dpp v218, v218, v218 row_ror:8 row_mask:0xf bank_mask:0xf bound_ctrl:1
	v_cmp_eq_u32_e32 vcc, v207, v218
	v_cndmask_b32_e64 v215, v215, v218, s[28:29]
	s_nop 0
	v_addc_co_u32_e64 v213, s[0:1], v213, v216, vcc
	v_add_lshl_u32 v216, v213, v0, 2
	ds_bpermute_b32 v216, v216, v206
	v_cndmask_b32_e64 v218, 0, 1, vcc
	s_waitcnt lgkmcnt(0)
	v_add_f32_e32 v216, v161, v216
	v_not_b32_e32 v219, v216
	v_or_b32_e32 v220, 0x80000000, v216
	v_cmp_gt_i32_e64 s[0:1], 0, v216
	s_nop 1
	v_cndmask_b32_e64 v216, v220, v219, s[0:1]
	v_and_or_b32 v216, v216, s52, v171
	v_bitop3_b32 v216, v216, s89, v213 bitop3:0x36
	v_cndmask_b32_e32 v207, v207, v216, vcc
	s_nop 1
	v_max_u32_dpp v216, v207, v207 row_ror:1 row_mask:0xf bank_mask:0xf bound_ctrl:1
	s_nop 1
	v_max_u32_dpp v216, v216, v216 row_ror:2 row_mask:0xf bank_mask:0xf bound_ctrl:1
	s_nop 1
	v_max_u32_dpp v216, v216, v216 row_ror:4 row_mask:0xf bank_mask:0xf bound_ctrl:1
	s_nop 1
	v_max_u32_dpp v216, v216, v216 row_ror:8 row_mask:0xf bank_mask:0xf bound_ctrl:1
	v_cmp_eq_u32_e32 vcc, v207, v216
	v_cndmask_b32_e64 v215, v215, v216, s[30:31]
	s_nop 0
	v_addc_co_u32_e64 v217, s[0:1], v217, v218, vcc
	v_add_lshl_u32 v218, v217, v0, 2
	ds_bpermute_b32 v218, v218, v206
	v_cndmask_b32_e64 v216, 0, 1, vcc
	s_waitcnt lgkmcnt(0)
	v_add_f32_e32 v218, v161, v218
	v_not_b32_e32 v219, v218
	v_or_b32_e32 v220, 0x80000000, v218
	v_cmp_gt_i32_e64 s[0:1], 0, v218
	s_nop 1
	v_cndmask_b32_e64 v218, v220, v219, s[0:1]
	v_and_or_b32 v218, v218, s52, v171
	v_bitop3_b32 v218, v218, s89, v217 bitop3:0x36
	v_cndmask_b32_e32 v207, v207, v218, vcc
	s_nop 1
	v_max_u32_dpp v218, v207, v207 row_ror:1 row_mask:0xf bank_mask:0xf bound_ctrl:1
	s_nop 1
	v_max_u32_dpp v218, v218, v218 row_ror:2 row_mask:0xf bank_mask:0xf bound_ctrl:1
	s_nop 1
	v_max_u32_dpp v218, v218, v218 row_ror:4 row_mask:0xf bank_mask:0xf bound_ctrl:1
	s_nop 1
	v_max_u32_dpp v218, v218, v218 row_ror:8 row_mask:0xf bank_mask:0xf bound_ctrl:1
	v_cmp_eq_u32_e32 vcc, v207, v218
	v_cndmask_b32_e64 v215, v215, v218, s[34:35]
	s_nop 0
	v_addc_co_u32_e64 v213, s[0:1], v213, v216, vcc
	v_add_lshl_u32 v216, v213, v0, 2
	ds_bpermute_b32 v216, v216, v206
	v_cndmask_b32_e64 v218, 0, 1, vcc
	s_waitcnt lgkmcnt(0)
	v_add_f32_e32 v216, v161, v216
	v_not_b32_e32 v219, v216
	v_or_b32_e32 v220, 0x80000000, v216
	v_cmp_gt_i32_e64 s[0:1], 0, v216
	s_nop 1
	v_cndmask_b32_e64 v216, v220, v219, s[0:1]
	v_and_or_b32 v216, v216, s52, v171
	v_bitop3_b32 v216, v216, s89, v213 bitop3:0x36
	v_cndmask_b32_e32 v207, v207, v216, vcc
	s_nop 1
	v_max_u32_dpp v216, v207, v207 row_ror:1 row_mask:0xf bank_mask:0xf bound_ctrl:1
	s_nop 1
	v_max_u32_dpp v216, v216, v216 row_ror:2 row_mask:0xf bank_mask:0xf bound_ctrl:1
	s_nop 1
	v_max_u32_dpp v216, v216, v216 row_ror:4 row_mask:0xf bank_mask:0xf bound_ctrl:1
	s_nop 1
	v_max_u32_dpp v216, v216, v216 row_ror:8 row_mask:0xf bank_mask:0xf bound_ctrl:1
	v_cmp_eq_u32_e32 vcc, v207, v216
	v_cndmask_b32_e64 v215, v215, v216, s[36:37]
	s_nop 0
	v_addc_co_u32_e64 v217, s[0:1], v217, v218, vcc
	v_add_lshl_u32 v218, v217, v0, 2
	ds_bpermute_b32 v218, v218, v206
	v_cndmask_b32_e64 v216, 0, 1, vcc
	s_waitcnt lgkmcnt(0)
	v_add_f32_e32 v218, v161, v218
	v_not_b32_e32 v219, v218
	v_or_b32_e32 v220, 0x80000000, v218
	v_cmp_gt_i32_e64 s[0:1], 0, v218
	s_nop 1
	v_cndmask_b32_e64 v218, v220, v219, s[0:1]
	v_and_or_b32 v218, v218, s52, v171
	v_bitop3_b32 v218, v218, s89, v217 bitop3:0x36
	v_cndmask_b32_e32 v207, v207, v218, vcc
	s_nop 1
	v_max_u32_dpp v218, v207, v207 row_ror:1 row_mask:0xf bank_mask:0xf bound_ctrl:1
	s_nop 1
	v_max_u32_dpp v218, v218, v218 row_ror:2 row_mask:0xf bank_mask:0xf bound_ctrl:1
	s_nop 1
	v_max_u32_dpp v218, v218, v218 row_ror:4 row_mask:0xf bank_mask:0xf bound_ctrl:1
	s_nop 1
	v_max_u32_dpp v218, v218, v218 row_ror:8 row_mask:0xf bank_mask:0xf bound_ctrl:1
	v_cmp_eq_u32_e32 vcc, v207, v218
	v_cndmask_b32_e64 v215, v215, v218, s[38:39]
	s_nop 0
	v_addc_co_u32_e64 v213, s[0:1], v213, v216, vcc
	v_add_lshl_u32 v216, v213, v0, 2
	ds_bpermute_b32 v216, v216, v206
	v_cndmask_b32_e64 v218, 0, 1, vcc
	s_waitcnt lgkmcnt(0)
; __device__ __forceinline__ void peer_topk(const u32x4 (&scv)[4], const int lane, int (&eidx)[2], float (&gate)[2]) {
;     ...
;       s2p = __uint_as_float((unsigned)__builtin_amdgcn_ds_bpermute((rbase + pcl) * 4, (int)__float_as_uint(s2)));
;       const unsigned nk = (f_ord(s1 + s2p) & ~0xFFu) | (unsigned)(255 - (li * 16 + pcl));
;       hk = win ? (ptr < 16 ? nk : 0u) : hk;
;     }
;     const float ts = f_deord(keep & ~0xFFu);
;     const int idx8 = 255 - (int)(keep & 0xFFu);
;     const int a = idx8 >> 4, bq = idx8 & 15;
;     const int e1 = __builtin_amdgcn_ds_bpermute((rbase + a) * 4, i1);
;     const int e2 = __builtin_amdgcn_ds_bpermute((rbase + bq) * 4, i2);
;     eidx[hp2] = e1 * 128 + e2;
;     const float tmax = f_deord(rowmax_u(keep) & ~0xFFu);
;     const float ex = __expf(ts - tmax);
;     const float sm = rowsum_f(ex);
;     gate[hp2] = ex / sm;
	v_add_f32_e32 v216, v161, v216
	v_not_b32_e32 v219, v216
	v_or_b32_e32 v220, 0x80000000, v216
	v_cmp_gt_i32_e64 s[0:1], 0, v216
	s_nop 1
	v_cndmask_b32_e64 v216, v220, v219, s[0:1]
	v_and_or_b32 v216, v216, s52, v171
	v_bitop3_b32 v216, v216, s89, v213 bitop3:0x36
	v_cndmask_b32_e32 v207, v207, v216, vcc
	s_nop 1
	v_max_u32_dpp v216, v207, v207 row_ror:1 row_mask:0xf bank_mask:0xf bound_ctrl:1
	s_nop 1
	v_max_u32_dpp v216, v216, v216 row_ror:2 row_mask:0xf bank_mask:0xf bound_ctrl:1
	s_nop 1
	v_max_u32_dpp v216, v216, v216 row_ror:4 row_mask:0xf bank_mask:0xf bound_ctrl:1
	s_nop 1
	v_max_u32_dpp v216, v216, v216 row_ror:8 row_mask:0xf bank_mask:0xf bound_ctrl:1
	v_cmp_eq_u32_e32 vcc, v207, v216
	v_cndmask_b32_e64 v215, v215, v216, s[40:41]
	s_nop 0
	v_addc_co_u32_e64 v217, s[0:1], v217, v218, vcc
	v_add_lshl_u32 v218, v217, v0, 2
	ds_bpermute_b32 v218, v218, v206
	v_cndmask_b32_e64 v216, 0, 1, vcc
	s_waitcnt lgkmcnt(0)
	v_add_f32_e32 v218, v161, v218
	v_not_b32_e32 v219, v218
	v_or_b32_e32 v220, 0x80000000, v218
	v_cmp_gt_i32_e64 s[0:1], 0, v218
	s_nop 1
	v_cndmask_b32_e64 v218, v220, v219, s[0:1]
	v_and_or_b32 v218, v218, s52, v171
	v_bitop3_b32 v217, v218, s89, v217 bitop3:0x36
	v_cndmask_b32_e32 v207, v207, v217, vcc
	s_nop 1
	v_max_u32_dpp v217, v207, v207 row_ror:1 row_mask:0xf bank_mask:0xf bound_ctrl:1
	s_nop 1
	v_max_u32_dpp v217, v217, v217 row_ror:2 row_mask:0xf bank_mask:0xf bound_ctrl:1
	s_nop 1
	v_max_u32_dpp v217, v217, v217 row_ror:4 row_mask:0xf bank_mask:0xf bound_ctrl:1
	s_nop 1
	v_max_u32_dpp v217, v217, v217 row_ror:8 row_mask:0xf bank_mask:0xf bound_ctrl:1
	v_cmp_eq_u32_e32 vcc, v207, v217
	v_cndmask_b32_e64 v215, v215, v217, s[42:43]
	s_nop 0
	v_addc_co_u32_e64 v213, s[0:1], v213, v216, vcc
	v_add_lshl_u32 v216, v213, v0, 2
	ds_bpermute_b32 v206, v216, v206
	s_waitcnt lgkmcnt(0)
	v_add_f32_e32 v161, v161, v206
	v_not_b32_e32 v206, v161
	v_or_b32_e32 v216, 0x80000000, v161
	v_cmp_gt_i32_e64 s[0:1], 0, v161
	s_nop 1
	v_cndmask_b32_e64 v161, v216, v206, s[0:1]
	v_and_or_b32 v161, v161, s52, v171
	v_bitop3_b32 v161, v161, s89, v213 bitop3:0x36
	v_cndmask_b32_e32 v161, v207, v161, vcc
	s_nop 1
	v_max_u32_dpp v161, v161, v161 row_ror:1 row_mask:0xf bank_mask:0xf bound_ctrl:1
	s_nop 1
	v_max_u32_dpp v161, v161, v161 row_ror:2 row_mask:0xf bank_mask:0xf bound_ctrl:1
	s_nop 1
	v_max_u32_dpp v161, v161, v161 row_ror:4 row_mask:0xf bank_mask:0xf bound_ctrl:1
	s_nop 1
	v_max_u32_dpp v161, v161, v161 row_ror:8 row_mask:0xf bank_mask:0xf bound_ctrl:1
	v_cndmask_b32_e64 v161, v215, v161, s[44:45]
	v_not_b32_e32 v206, v161
	v_lshrrev_b32_e32 v206, 4, v206
	v_and_or_b32 v206, v206, 15, v0
	v_lshlrev_b32_e32 v206, 2, v206
	ds_bpermute_b32 v157, v206, v157
	v_bitop3_b32 v206, v161, v0, 15 bitop3:0xce
	v_lshlrev_b32_e32 v206, 2, v206
	ds_bpermute_b32 v159, v206, v159
	v_cmp_lt_i32_e64 s[0:1], -1, v161
	v_and_b32_e32 v207, 0xffffff00, v161
	s_waitcnt lgkmcnt(0)
	v_lshl_add_u32 v157, v157, 7, v159
	v_max_u32_dpp v159, v161, v161 row_ror:1 row_mask:0xf bank_mask:0xf bound_ctrl:1
	v_cndmask_b32_e64 v161, v245, -1, s[0:1]
	v_xor_b32_e32 v161, v161, v207
	v_max_u32_dpp v159, v159, v159 row_ror:2 row_mask:0xf bank_mask:0xf bound_ctrl:1
	v_mov_b32_e32 v207, 0
	s_nop 0
	v_max_u32_dpp v159, v159, v159 row_ror:4 row_mask:0xf bank_mask:0xf bound_ctrl:1
	s_nop 1
	v_max_u32_dpp v159, v159, v159 row_ror:8 row_mask:0xf bank_mask:0xf bound_ctrl:1
	v_cmp_lt_i32_e32 vcc, -1, v159
	v_and_b32_e32 v206, 0xffffff00, v159
	s_nop 0
	v_cndmask_b32_e64 v159, v245, -1, vcc
	v_xor_b32_e32 v159, v159, v206
	v_sub_f32_e32 v159, v161, v159
	v_mul_f32_e32 v159, 0x3fb8aa3b, v159
	v_exp_f32_e32 v159, v159
	v_mov_b32_e32 v161, 0
	v_mov_b32_e32 v206, 0
	s_nop 0
	v_mov_b32_dpp v161, v159 row_ror:1 row_mask:0xf bank_mask:0xf
	v_pk_add_f32 v[160:161], v[158:159], v[160:161]
	s_nop 1
	v_mov_b32_dpp v206, v160 row_ror:2 row_mask:0xf bank_mask:0xf
	v_mov_b32_dpp v207, v161 row_ror:2 row_mask:0xf bank_mask:0xf
	v_pk_add_f32 v[160:161], v[160:161], v[206:207]
	v_mov_b32_e32 v206, 0
	v_mov_b32_e32 v207, 0
	s_nop 0
	v_mov_b32_dpp v206, v160 row_ror:4 row_mask:0xf bank_mask:0xf
	v_mov_b32_dpp v207, v161 row_ror:4 row_mask:0xf bank_mask:0xf
	v_pk_add_f32 v[160:161], v[160:161], v[206:207]
	v_mov_b32_e32 v206, 0
	v_mov_b32_e32 v207, 0
	s_nop 0
	v_mov_b32_dpp v206, v160 row_ror:8 row_mask:0xf bank_mask:0xf
	v_mov_b32_dpp v207, v161 row_ror:8 row_mask:0xf bank_mask:0xf
	v_pk_add_f32 v[160:161], v[160:161], v[206:207]
	s_nop 0
	v_div_scale_f32 v206, s[0:1], v161, v161, v159
	v_rcp_f32_e32 v207, v206
	s_nop 0
	v_fma_f32 v213, -v206, v207, 1.0
	v_fmac_f32_e32 v207, v213, v207
	v_div_scale_f32 v213, vcc, v159, v161, v159
	v_mul_f32_e32 v215, v213, v207
	v_fma_f32 v216, -v206, v215, v213
	v_fmac_f32_e32 v215, v216, v207
	v_fma_f32 v206, -v206, v215, v213
	v_div_fmas_f32 v206, v206, v207, v215
	v_div_fixup_f32 v159, v206, v161, v159
	v_div_scale_f32 v161, s[0:1], v160, v160, v158
	v_rcp_f32_e32 v206, v161
	s_nop 0
	v_fma_f32 v207, -v161, v206, 1.0
	v_fmac_f32_e32 v206, v207, v206
	v_div_scale_f32 v207, vcc, v158, v160, v158
	v_mul_f32_e32 v213, v207, v206
	v_fma_f32 v215, -v161, v213, v207
	v_fmac_f32_e32 v213, v215, v206
	v_fma_f32 v161, -v161, v213, v207
	v_div_fmas_f32 v161, v161, v206, v213
	v_div_fixup_f32 v158, v161, v160, v158

; __device__ void peer_u(const P& p, int layer, int tok, char* smem, const int (&eidx)[2], const float (&gate)[2],
;                        const u32x4 (&scnext)[4], const bool has_next, int (&eidx_n)[2], float (&gate_n)[2]) {
;     ...
;     const float su = SU[eidx[h2]], sv = SV[eidx[h2]];
;     float hreg = 0.f;
;     for (int b2 = 0; b2 < 2; ++b2) {
;       u32x4 uu[16];
;       const int lh = lane >> 5, l5 = lane & 31;
; #pragma unroll
;       for (int q = 0; q < 16; ++q) {
;         const int e0 = __builtin_amdgcn_readlane(eidx[h2], b2 * 32 + 2 * q);
;         const int e1 = __builtin_amdgcn_readlane(eidx[h2], b2 * 32 + 2 * q + 1);
;         const int e = lh ? e1 : e0;
;         uu[q] = ((const u32x4*)(U4 + (size_t)e * 512))[l5];
;       }
;       if (h2 == 0 && b2 == 0 && has_next) peer_topk(scnext, lane, eidx_n, gate_n);
; #pragma unroll
;       for (int hh = 0; hh < 2; ++hh) {
; #pragma unroll
;         for (int q = 0; q < 8; ++q) *(u32x4*)(lw + (2 * q + lh) * 544 + l5 * 16) = uu[hh * 8 + q];
;         f32x4 acc = {0.f, 0.f, 0.f, 0.f};
; #pragma unroll
;         for (int s8 = 0; s8 < 8; ++s8) {
;           const u32x4 a = *(const u32x4*)(lw + li * 544 + s8 * 64 + rw * 16);
;           const i32x8 av = {(int)a.x, (int)a.y, (int)a.z, (int)a.w, 0, 0, 0, 0};
;           acc = __builtin_amdgcn_mfma_scale_f32_16x16x128_f8f6f4(av, tq[s8], acc, 4, 0, 0, 0x7f7f7f7f, 0, 0x7f7f7f7f);
;         }
;         const int lr2 = li & 3;
;         const float sel = lr2 == 0 ? acc[0] : lr2 == 1 ? acc[1] : lr2 == 2 ? acc[2] : acc[3];
;         const float val = __uint_as_float((unsigned)__builtin_amdgcn_ds_bpermute(((li >> 2) * 16 + li) * 4, (int)__float_as_uint(sel)));
;         hreg = (rw == b2 * 2 + hh) ? val : hreg;
;       }
;     }
;     const float hid = hreg * su;
;     const float ge = 0.5f * hid * (1.f + erff(hid * 0.70710678118654752f));
.LBB0_1020:
	s_or_saveexec_b64 s[0:1], s[0:1]
	s_mov_b32 s50, 0x40000
	s_xor_b64 exec, exec, s[0:1]
	v_mul_f32_e32 v84, v0, v0
	v_fmamk_f32 v85, v84, 0xba1345e1, v240
	v_fmaak_f32 v85, v84, v85, 0xbcdac9b8
	v_fmaak_f32 v85, v84, v85, 0x3de703be
	v_fmaak_f32 v85, v84, v85, 0xbec09330
	v_fmaak_f32 v84, v84, v85, 0x3e0375d0
	v_fma_f32 v121, |v0|, v84, |v0|
	s_or_b64 exec, exec, s[0:1]
	v_lshlrev_b32_e32 v253, 9, v3
	v_add_u32_e32 v222, 56, v221
	ds_bpermute_b32 v222, v222, v253
	v_add_u32_e32 v224, 48, v221
	ds_bpermute_b32 v224, v224, v253
	v_add_u32_e32 v226, 40, v221
	ds_bpermute_b32 v226, v226, v253
	v_add_u32_e32 v228, 32, v221
	ds_bpermute_b32 v228, v228, v253
	v_add_u32_e32 v230, 24, v221
	ds_bpermute_b32 v230, v230, v253
	v_add_u32_e32 v232, 16, v221
	ds_bpermute_b32 v232, v232, v253
	v_add_u32_e32 v234, 0, v221
	ds_bpermute_b32 v234, v234, v253
	v_add_u32_e32 v236, 8, v221
	ds_bpermute_b32 v236, v236, v253
	s_waitcnt lgkmcnt(0)
	v_lshl_add_u64 v[112:113], v[222:223], 0, v[154:155]
	v_lshl_add_u64 v[100:101], v[226:227], 0, v[154:155]
	v_lshl_add_u64 v[104:105], v[228:229], 0, v[154:155]
	v_lshl_add_u64 v[92:93], v[230:231], 0, v[154:155]
	v_lshl_add_u64 v[96:97], v[232:233], 0, v[154:155]
	v_lshl_add_u64 v[84:85], v[236:237], 0, v[154:155]
	v_lshl_add_u64 v[88:89], v[234:235], 0, v[154:155]
	v_lshl_add_u64 v[108:109], v[224:225], 0, v[154:155]
	global_load_dwordx4 v[84:87], v[84:85], off
	s_nop 0
	global_load_dwordx4 v[88:91], v[88:89], off
	s_nop 0
	global_load_dwordx4 v[92:95], v[92:93], off
	s_nop 0
	global_load_dwordx4 v[96:99], v[96:97], off
	s_nop 0
	global_load_dwordx4 v[100:103], v[100:101], off
	s_nop 0
	global_load_dwordx4 v[104:107], v[104:105], off
	s_nop 0
	global_load_dwordx4 v[108:111], v[108:109], off
	s_nop 0
	global_load_dwordx4 v[112:115], v[112:113], off
	v_lshlrev_b32_e32 v253, 9, v3
	v_add_u32_e32 v222, 64, v221
	ds_bpermute_b32 v222, v222, v253
	v_add_u32_e32 v224, 72, v221
	ds_bpermute_b32 v224, v224, v253
	v_add_u32_e32 v226, 80, v221
	ds_bpermute_b32 v226, v226, v253
	v_add_u32_e32 v228, 88, v221
	ds_bpermute_b32 v228, v228, v253
	v_add_u32_e32 v230, 96, v221
	ds_bpermute_b32 v230, v230, v253
	v_add_u32_e32 v232, 104, v221
	ds_bpermute_b32 v232, v232, v253
	v_add_u32_e32 v234, 112, v221
	ds_bpermute_b32 v234, v234, v253
	v_add_u32_e32 v236, 120, v221
	ds_bpermute_b32 v236, v236, v253
	v_cmp_lt_i32_e32 vcc, 0, v167
	s_waitcnt lgkmcnt(0)
	v_lshl_add_u64 v[116:117], v[236:237], 0, v[154:155]
	s_waitcnt vmcnt(6)
	ds_write_b128 v169, v[88:91]
	ds_write_b128 v169, v[84:87] offset:1088
	s_waitcnt vmcnt(4)
	ds_write_b128 v169, v[96:99] offset:2176
	ds_write_b128 v169, v[92:95] offset:3264
	s_waitcnt vmcnt(2)
	ds_write_b128 v169, v[104:107] offset:4352
	ds_write_b128 v169, v[100:103] offset:5440
	s_waitcnt vmcnt(1)
	ds_write_b128 v169, v[108:111] offset:6528
	s_waitcnt vmcnt(0)
	ds_write_b128 v169, v[112:115] offset:7616
	ds_read_b128 v[84:87], v168
	ds_read_b128 v[88:91], v168 offset:64
	s_waitcnt lgkmcnt(1)
	v_mfma_scale_f32_16x16x128_f8f6f4 v[84:87], v[84:87], v[20:27], 0, v238, v238 op_sel_hi:[0,0,0] cbsz:4
	s_waitcnt lgkmcnt(0)
	v_mfma_scale_f32_16x16x128_f8f6f4 v[84:87], v[88:91], v[28:35], v[84:87], v238, v238 op_sel_hi:[0,0,0] cbsz:4
	ds_read_b128 v[88:91], v168 offset:128
	ds_read_b128 v[92:95], v168 offset:192
	s_waitcnt lgkmcnt(1)
	v_mfma_scale_f32_16x16x128_f8f6f4 v[84:87], v[88:91], v[36:43], v[84:87], v238, v238 op_sel_hi:[0,0,0] cbsz:4
	s_waitcnt lgkmcnt(0)
	v_mfma_scale_f32_16x16x128_f8f6f4 v[84:87], v[92:95], v[44:51], v[84:87], v238, v238 op_sel_hi:[0,0,0] cbsz:4
	ds_read_b128 v[88:91], v168 offset:256
	ds_read_b128 v[92:95], v168 offset:320
	v_lshl_add_u64 v[100:101], v[228:229], 0, v[154:155]
	v_lshl_add_u64 v[104:105], v[230:231], 0, v[154:155]
	v_lshl_add_u64 v[108:109], v[232:233], 0, v[154:155]
	v_lshl_add_u64 v[112:113], v[234:235], 0, v[154:155]
	s_waitcnt lgkmcnt(1)
	v_mfma_scale_f32_16x16x128_f8f6f4 v[84:87], v[88:91], v[52:59], v[84:87], v238, v238 op_sel_hi:[0,0,0] cbsz:4
	ds_read_b128 v[88:91], v168 offset:384
	s_waitcnt lgkmcnt(1)
	v_mfma_scale_f32_16x16x128_f8f6f4 v[84:87], v[92:95], v[60:67], v[84:87], v238, v238 op_sel_hi:[0,0,0] cbsz:4
	ds_read_b128 v[92:95], v168 offset:448
	s_waitcnt lgkmcnt(1)
	v_mfma_scale_f32_16x16x128_f8f6f4 v[84:87], v[88:91], v[68:75], v[84:87], v238, v238 op_sel_hi:[0,0,0] cbsz:4
	v_ashrrev_i32_e32 v89, 31, v3
	v_mov_b32_e32 v88, v3
	v_lshlrev_b64 v[88:89], 2, v[88:89]
	v_lshl_add_u64 v[90:91], s[68:69], 0, v[88:89]
	v_lshl_add_u64 v[88:89], s[70:71], 0, v[88:89]
	s_waitcnt lgkmcnt(0)
	v_mfma_scale_f32_16x16x128_f8f6f4 v[84:87], v[92:95], v[76:83], v[84:87], v238, v238 op_sel_hi:[0,0,0] cbsz:4
	v_lshl_add_u64 v[92:93], v[222:223], 0, v[154:155]
	global_load_dword v123, v[90:91], off
	global_load_dword v122, v[88:89], off
	s_nop 0
	global_load_dwordx4 v[88:91], v[92:93], off
	v_lshl_add_u64 v[92:93], v[224:225], 0, v[154:155]
	v_lshl_add_u64 v[96:97], v[226:227], 0, v[154:155]
	global_load_dwordx4 v[92:95], v[92:93], off
	s_nop 0
	global_load_dwordx4 v[96:99], v[96:97], off
	s_nop 0
	global_load_dwordx4 v[100:103], v[100:101], off
	s_nop 0
	global_load_dwordx4 v[104:107], v[104:105], off
	s_nop 0
	global_load_dwordx4 v[108:111], v[108:109], off
	s_nop 0
	global_load_dwordx4 v[112:115], v[112:113], off
	s_nop 0
	global_load_dwordx4 v[116:119], v[116:117], off
	s_and_saveexec_b64 s[0:1], vcc
	s_xor_b64 s[0:1], exec, s[0:1]
	s_mov_b64 s[68:69], s[92:93]
	s_mov_b32 s70, s46
	s_mov_b32 s71, s47
	s_mov_b32 s76, s86
	s_mov_b32 s77, s79
	s_mov_b32 s86, s65
	s_mov_b32 s92, s33
	s_movk_i32 s33, 0x70
	s_mov_b32 s93, 0x10000
	s_mov_b32 s46, 0x20000
	s_mov_b32 s47, 0x30000
	s_cbranch_execz .LBB0_1026
	v_cmp_ne_u32_e32 vcc, 1, v167
	v_mov_b32_e32 v84, v85
	s_and_saveexec_b64 s[12:13], vcc
	s_xor_b64 s[12:13], exec, s[12:13]
	v_cndmask_b32_e64 v84, v87, v86, s[8:9]
	s_andn2_saveexec_b64 s[12:13], s[12:13]
	s_or_b64 exec, exec, s[12:13]

; __device__ void peer_u(const P& p, int layer, int tok, char* smem, const int (&eidx)[2], const float (&gate)[2],
;                        const u32x4 (&scnext)[4], const bool has_next, int (&eidx_n)[2], float (&gate_n)[2]) {
;     ...
;     for (int b2 = 0; b2 < 2; ++b2) {
;       u32x4 uu[16];
;       const int lh = lane >> 5, l5 = lane & 31;
; #pragma unroll
;       for (int q = 0; q < 16; ++q) {
;         const int e0 = __builtin_amdgcn_readlane(eidx[h2], b2 * 32 + 2 * q);
;         const int e1 = __builtin_amdgcn_readlane(eidx[h2], b2 * 32 + 2 * q + 1);
;         const int e = lh ? e1 : e0;
;         uu[q] = ((const u32x4*)(U4 + (size_t)e * 512))[l5];
;       }
;       if (h2 == 0 && b2 == 0 && has_next) peer_topk(scnext, lane, eidx_n, gate_n);
; #pragma unroll
;       for (int hh = 0; hh < 2; ++hh) {
; #pragma unroll
;         for (int q = 0; q < 8; ++q) *(u32x4*)(lw + (2 * q + lh) * 544 + l5 * 16) = uu[hh * 8 + q];
;         f32x4 acc = {0.f, 0.f, 0.f, 0.f};
; #pragma unroll
;         for (int s8 = 0; s8 < 8; ++s8) {
;           const u32x4 a = *(const u32x4*)(lw + li * 544 + s8 * 64 + rw * 16);
;           const i32x8 av = {(int)a.x, (int)a.y, (int)a.z, (int)a.w, 0, 0, 0, 0};
;           acc = __builtin_amdgcn_mfma_scale_f32_16x16x128_f8f6f4(av, tq[s8], acc, 4, 0, 0, 0x7f7f7f7f, 0, 0x7f7f7f7f);
;         }
;         const int lr2 = li & 3;
;         const float sel = lr2 == 0 ? acc[0] : lr2 == 1 ? acc[1] : lr2 == 2 ? acc[2] : acc[3];
;         const float val = __uint_as_float((unsigned)__builtin_amdgcn_ds_bpermute(((li >> 2) * 16 + li) * 4, (int)__float_as_uint(sel)));
;         hreg = (rw == b2 * 2 + hh) ? val : hreg;
.LBB0_1030:
	s_andn2_saveexec_b64 s[0:1], s[0:1]
	s_or_b64 exec, exec, s[0:1]
	v_lshlrev_b32_e32 v253, 9, v3
	v_add_u32_e32 v222, 184, v221
	ds_bpermute_b32 v222, v222, v253
	v_add_u32_e32 v224, 176, v221
	ds_bpermute_b32 v224, v224, v253
	v_add_u32_e32 v226, 168, v221
	ds_bpermute_b32 v226, v226, v253
	v_add_u32_e32 v228, 160, v221
	ds_bpermute_b32 v228, v228, v253
	v_add_u32_e32 v230, 152, v221
	ds_bpermute_b32 v230, v230, v253
	v_add_u32_e32 v232, 144, v221
	ds_bpermute_b32 v232, v232, v253
	v_add_u32_e32 v234, 136, v221
	ds_bpermute_b32 v234, v234, v253
	v_add_u32_e32 v236, 128, v221
	ds_bpermute_b32 v236, v236, v253
	s_nop 3
	s_waitcnt lgkmcnt(0)
	v_lshl_add_u64 v[114:115], v[222:223], 0, v[154:155]
	v_lshl_add_u64 v[102:103], v[226:227], 0, v[154:155]
	v_lshl_add_u64 v[106:107], v[228:229], 0, v[154:155]
	v_lshl_add_u64 v[94:95], v[230:231], 0, v[154:155]
	v_lshl_add_u64 v[98:99], v[232:233], 0, v[154:155]
	v_lshl_add_u64 v[86:87], v[234:235], 0, v[154:155]
	v_lshl_add_u64 v[90:91], v[236:237], 0, v[154:155]
	v_lshl_add_u64 v[110:111], v[224:225], 0, v[154:155]
	global_load_dwordx4 v[86:89], v[86:87], off
	s_nop 0
	global_load_dwordx4 v[90:93], v[90:91], off
	s_nop 0
	global_load_dwordx4 v[94:97], v[94:95], off
	s_nop 0
	global_load_dwordx4 v[98:101], v[98:99], off
	s_nop 0
	global_load_dwordx4 v[102:105], v[102:103], off
	s_nop 0
	global_load_dwordx4 v[106:109], v[106:107], off
	s_nop 0
	global_load_dwordx4 v[110:113], v[110:111], off
	s_nop 0
	global_load_dwordx4 v[114:117], v[114:115], off
	ds_bpermute_b32 v125, v166, v84
	v_lshlrev_b32_e32 v253, 9, v3
	v_add_u32_e32 v222, 192, v221
	ds_bpermute_b32 v222, v222, v253
	v_add_u32_e32 v224, 200, v221
	ds_bpermute_b32 v224, v224, v253
	v_add_u32_e32 v226, 208, v221
	ds_bpermute_b32 v226, v226, v253
	v_add_u32_e32 v228, 216, v221
	ds_bpermute_b32 v228, v228, v253
	v_add_u32_e32 v230, 224, v221
	ds_bpermute_b32 v230, v230, v253
	v_add_u32_e32 v232, 232, v221
	ds_bpermute_b32 v232, v232, v253
	v_add_u32_e32 v234, 240, v221
	ds_bpermute_b32 v234, v234, v253
	v_add_u32_e32 v236, 248, v221
	ds_bpermute_b32 v236, v236, v253
	v_cmp_lt_i32_e32 vcc, 0, v167
	s_waitcnt vmcnt(6)
	ds_write_b128 v169, v[90:93]
	ds_write_b128 v169, v[86:89] offset:1088
	s_waitcnt vmcnt(4)
	ds_write_b128 v169, v[98:101] offset:2176
	ds_write_b128 v169, v[94:97] offset:3264
	s_waitcnt vmcnt(2)
	ds_write_b128 v169, v[106:109] offset:4352
	ds_write_b128 v169, v[102:105] offset:5440
	s_waitcnt vmcnt(1)
	ds_write_b128 v169, v[110:113] offset:6528
	s_waitcnt vmcnt(0)
	ds_write_b128 v169, v[114:117] offset:7616
	ds_read_b128 v[86:89], v168
	ds_read_b128 v[90:93], v168 offset:64
	s_waitcnt lgkmcnt(1)
	v_mfma_scale_f32_16x16x128_f8f6f4 v[86:89], v[86:89], v[20:27], 0, v238, v238 op_sel_hi:[0,0,0] cbsz:4
	s_waitcnt lgkmcnt(0)
	v_mfma_scale_f32_16x16x128_f8f6f4 v[86:89], v[90:93], v[28:35], v[86:89], v238, v238 op_sel_hi:[0,0,0] cbsz:4
	ds_read_b128 v[90:93], v168 offset:128
	ds_read_b128 v[94:97], v168 offset:192
	s_waitcnt lgkmcnt(1)
	v_mfma_scale_f32_16x16x128_f8f6f4 v[86:89], v[90:93], v[36:43], v[86:89], v238, v238 op_sel_hi:[0,0,0] cbsz:4
	s_waitcnt lgkmcnt(0)
	v_mfma_scale_f32_16x16x128_f8f6f4 v[86:89], v[94:97], v[44:51], v[86:89], v238, v238 op_sel_hi:[0,0,0] cbsz:4
	ds_read_b128 v[90:93], v168 offset:256
	ds_read_b128 v[94:97], v168 offset:320
	s_waitcnt lgkmcnt(0)
	v_lshl_add_u64 v[100:101], v[228:229], 0, v[154:155]
	s_waitcnt lgkmcnt(1)
	v_mfma_scale_f32_16x16x128_f8f6f4 v[86:89], v[90:93], v[52:59], v[86:89], v238, v238 op_sel_hi:[0,0,0] cbsz:4
	ds_read_b128 v[90:93], v168 offset:384
	v_lshl_add_u64 v[104:105], v[230:231], 0, v[154:155]
	v_lshl_add_u64 v[108:109], v[232:233], 0, v[154:155]
	v_lshl_add_u64 v[112:113], v[234:235], 0, v[154:155]
	v_lshl_add_u64 v[116:117], v[236:237], 0, v[154:155]
	s_waitcnt lgkmcnt(1)
	v_mfma_scale_f32_16x16x128_f8f6f4 v[84:87], v[94:97], v[60:67], v[86:89], v238, v238 op_sel_hi:[0,0,0] cbsz:4
	ds_read_b128 v[94:97], v168 offset:448
	s_waitcnt lgkmcnt(1)
	v_mfma_scale_f32_16x16x128_f8f6f4 v[84:87], v[90:93], v[68:75], v[84:87], v238, v238 op_sel_hi:[0,0,0] cbsz:4
	s_nop 3
	s_waitcnt lgkmcnt(0)
	v_mfma_scale_f32_16x16x128_f8f6f4 v[84:87], v[94:97], v[76:83], v[84:87], v238, v238 op_sel_hi:[0,0,0] cbsz:4
	v_lshl_add_u64 v[88:89], v[222:223], 0, v[154:155]
	v_lshl_add_u64 v[92:93], v[224:225], 0, v[154:155]
	v_lshl_add_u64 v[96:97], v[226:227], 0, v[154:155]
	global_load_dwordx4 v[88:91], v[88:89], off
	s_nop 0
	global_load_dwordx4 v[92:95], v[92:93], off
	s_nop 0
	global_load_dwordx4 v[96:99], v[96:97], off
	s_nop 0
	global_load_dwordx4 v[100:103], v[100:101], off
	s_nop 0
	global_load_dwordx4 v[104:107], v[104:105], off
	s_nop 0
	global_load_dwordx4 v[108:111], v[108:109], off
	s_nop 0
	global_load_dwordx4 v[112:115], v[112:113], off
	s_nop 0
	global_load_dwordx4 v[116:119], v[116:117], off
	s_and_saveexec_b64 s[0:1], vcc
	s_xor_b64 s[0:1], exec, s[0:1]
	s_cbranch_execz .LBB0_1034
	v_cmp_ne_u32_e32 vcc, 1, v167
	v_mov_b32_e32 v84, v85
	s_and_saveexec_b64 s[10:11], vcc
	s_xor_b64 s[10:11], exec, s[10:11]
	v_cndmask_b32_e64 v84, v87, v86, s[8:9]
	s_andn2_saveexec_b64 s[10:11], s[10:11]
	s_or_b64 exec, exec, s[10:11]
